# up-projection chain: dropped the per-wave L1 invalidate before the chain GEMM; gate-byte tile loads made agent-scope (sc1) instead
# speedup vs baseline: 1.0109x; 1.0109x over previous
; #define PG8_STAGE(bufoff, gbase, voff) do { _Pragma("unroll") for (int _i = 0; _i < 2; ++_i) \
;         __builtin_amdgcn_global_load_lds((const unsigned*)((const char*)(gbase) + (voff)[_i]), (PG8_LAS unsigned*)(lds + (bufoff) + ldsw + _i * 8192), 16, 0, 0); } while (0)
; #define PG8_BAR __builtin_amdgcn_s_barrier()
; #define GAS __attribute__((address_space(1)))
; __device__ __forceinline__ void l1_inv() { __builtin_amdgcn_fence(__ATOMIC_ACQUIRE, "agent"); }
; template <class Epi, class Sched, bool ALIGN_EPI = false, bool SP2 = false>
; __device__ __forceinline__ void gemm_phase(PG8_LAS unsigned char* lds, const Gemm g, const Sched& S, const Epi& E) {
;     ...
;     for (int i = 0; i < 2; ++i) { int R, C; stage_rc(tid * 16 + i * 8192, R, C); const int Rb = Epi::PERM ? ((R & ~31) + perm32(R & 31)) : R;
;         voffA[i] = (unsigned)(R * K + C) * 2u; voffB[i] = (unsigned)(Rb * K + C) * 2u; }
;     const size_t kstep = (size_t)(BK * 2);
;     const size_t hstep = (size_t)HALF * K * 2;
;     const size_t tstep = 2 * hstep;
;     const unsigned ldsw = (unsigned)wid * 1024u;
;     const int aoff = lds_byte(wr * 64 + fr, fq * 8), boff = lds_byte(wc * 32 + fr, fq * 8);
;     ...
;     Unit cur, nxt; int ui = 0;
;     if (!S.next(0, cur)) return;
;     f32x4 acc[2][2][4][2];
; #pragma unroll
;     for (int a = 0; a < 2; ++a)
; #pragma unroll
;         for (int b = 0; b < 2; ++b)
; #pragma unroll
;             for (int m = 0; m < 4; ++m)
; #pragma unroll
;                 for (int n = 0; n < 2; ++n) acc[a][b][m][n] = (f32x4){0.f, 0.f, 0.f, 0.f};
;     bf16x8 At[4][2], B0[2][2], B1[2][2];
;     const char* cA = (const char*)g.A + (size_t)cur.pm * tstep; const char* cB = (const char*)g.Bt + (size_t)cur.pn * tstep;
;     S.a_ready(cur);
;     if constexpr (SP2) {
;         PG8_STAGE(PG8_SB(0, 0), cB, voffB); PG8_STAGE(PG8_SB(0, 1), cB + hstep, voffB); PG8_STAGE(PG8_SA(0, 0), cA, voffA); PG8_STAGE(PG8_SA(0, 1), cA + hstep, voffA);
;         if (wr == 1) PG8_BAR;
; __global__ void __launch_bounds__(512, 2) mega_fwd(Args a) {
;     ...
;             { PH;
;               GAS unsigned char* Gt = (GAS unsigned char*)(ws + WS_MF + (size_t)blockIdx.x * 393216);
;               l1_inv();
;               run_gemm_chain(lds, (const bf16_t*)(ws + WS_OC), (const bf16_t*)(wl + WO_UP), 3 * T_TOK, 3 * DM, OCW, TriUnit{u.pm, u.pn, 256},
.LBB0_1024:
	s_waitcnt vmcnt(0)
	s_barrier
	s_load_dwordx2 s[8:9], s[84:85], 0x88
	s_mov_b32 s0, s65
	s_waitcnt lgkmcnt(0)
	s_mul_hi_i32 s1, s0, 0x2800000
	s_mul_i32 s0, s0, 0x2800000
	s_add_u32 s0, s8, s0
	s_addc_u32 s1, s9, s1
	s_add_u32 s26, s8, 0x12600000
	s_addc_u32 s27, s9, 0
	s_add_u32 s28, s0, 0xf00000
	s_addc_u32 s29, s1, 0
	s_movk_i32 s0, 0xc00
	s_mov_b32 s1, 0x30000
	s_movk_i32 s6, 0x180
	v_mov_b32_e32 v19, v230
	s_mov_b32 s0, 0x7fffffe0
	v_bfe_i32 v3, v19, 27, 1
	v_lshlrev_b32_e32 v2, 4, v19
	v_lshrrev_b32_e32 v3, 22, v3
	v_add_u32_e32 v3, v2, v3
	v_and_b32_e32 v3, 0xfffffc00, v3
	v_ashrrev_i32_e32 v1, 31, v19
	v_sub_u32_e32 v3, v2, v3
	v_lshrrev_b32_e32 v1, 26, v1
	v_lshrrev_b32_e32 v4, 4, v3
	v_add_u32_e32 v1, v19, v1
	v_bitop3_b32 v4, v4, v3, 32 bitop3:0x6c
	v_ashrrev_i32_e32 v3, 31, v3
	v_ashrrev_i32_e32 v1, 6, v1
	v_lshrrev_b32_e32 v3, 26, v3
	v_lshlrev_b32_e32 v5, 3, v1
	v_add_u32_e32 v3, v4, v3
	v_and_b32_e32 v5, -16, v5
	v_ashrrev_i32_e32 v3, 6, v3
	v_add_u32_e32 v5, v3, v5
	v_mul_i32_i24_e32 v6, 64, v3
	v_sub_u32_e32 v4, v4, v6
	v_lshlrev_b32_e32 v6, 1, v5
	v_lshrrev_b32_e32 v7, 2, v5
	v_and_b32_e32 v3, 3, v3
	v_lshlrev_b32_e32 v1, 5, v1
	v_ashrrev_i16_sdwa v4, v223, sext(v4) dst_sel:DWORD dst_unused:UNUSED_PAD src0_sel:DWORD src1_sel:BYTE_0
	v_and_b32_e32 v6, 24, v6
	v_and_b32_e32 v7, 4, v7
	v_and_or_b32 v3, v5, s0, v3
	v_and_b32_e32 v1, 32, v1
	v_bfe_i32 v14, v4, 0, 16
	v_or3_b32 v3, v3, v7, v6
	v_add_u32_e32 v4, v1, v14
	v_mul_lo_u32 v3, v3, s6
	v_add_u32_e32 v2, 0x2000, v2
	v_add_lshl_u32 v134, v3, v4, 1
	v_ashrrev_i32_e32 v3, 31, v2
	v_lshrrev_b32_e32 v3, 22, v3
	v_add_u32_e32 v3, v2, v3
	v_mul_lo_u32 v15, v5, s6
	v_ashrrev_i32_e32 v3, 10, v3
	v_add_lshl_u32 v132, v4, v15, 1
	v_mul_i32_i24_e32 v4, 0x400, v3
	v_sub_u32_e32 v2, v2, v4
	v_lshrrev_b32_e32 v4, 4, v2
	v_bitop3_b32 v2, v4, v2, 32 bitop3:0x6c
	v_ashrrev_i32_e32 v5, 31, v2
	v_lshrrev_b32_e32 v5, 26, v5
	v_lshlrev_b32_e32 v4, 3, v3
	v_add_u32_e32 v5, v2, v5
	v_and_b32_e32 v4, -16, v4
	v_ashrrev_i32_e32 v6, 6, v5
	v_add_u32_e32 v4, v6, v4
	v_and_b32_e32 v6, 3, v6
	s_ashr_i32 s7, s6, 31
	v_and_or_b32 v6, v4, s0, v6
	s_lshl_b64 s[0:1], s[6:7], 9
	s_mul_i32 s2, s0, s31
	s_mul_hi_u32 s3, s0, s52
	s_add_i32 s4, s3, s2
	s_lshr_b64 s[2:3], s[6:7], 23
	s_mul_i32 s3, s2, s52
	v_readfirstlane_b32 s12, v19
	s_add_i32 s10, s4, s3
	s_mul_i32 s3, s0, s34
	s_mul_hi_u32 s4, s0, s33
	s_ashr_i32 s13, s12, 6
	v_lshlrev_b32_e32 v3, 5, v3
	s_add_i32 s3, s4, s3
	s_mul_i32 s2, s2, s33
	v_and_b32_e32 v16, 32, v3
	v_and_b32_e32 v3, 0xc0, v5
	s_ashr_i32 s14, s12, 8
	s_lshl_b32 s30, s13, 10
	s_add_i32 s3, s3, s2
	s_mul_i32 s2, s0, s33
	v_sub_u32_e32 v2, v2, v3
	v_lshlrev_b32_e32 v3, 1, v4
	v_lshrrev_b32_e32 v5, 2, v4
	s_add_u32 s18, s28, s2
	v_ashrrev_i16_sdwa v2, v223, sext(v2) dst_sel:DWORD dst_unused:UNUSED_PAD src0_sel:DWORD src1_sel:BYTE_0
	v_and_b32_e32 v3, 24, v3
	v_and_b32_e32 v5, 4, v5
	s_addc_u32 s19, s29, s3
	s_add_i32 s31, s30, 0
	v_bfe_i32 v17, v2, 0, 16
	v_or3_b32 v3, v6, v5, v3
	s_add_i32 m0, s31, 0x10000
	v_add_u32_e32 v2, v16, v17
	v_mul_lo_u32 v3, v3, s6
	global_load_lds_dwordx4 v134, s[18:19]
	s_add_i32 m0, s31, 0x12000
	s_lshl_b64 s[2:3], s[6:7], 8
	v_add_lshl_u32 v138, v3, v2, 1
	s_add_u32 s4, s18, s2
	global_load_lds_dwordx4 v138, s[18:19]
	s_addc_u32 s5, s19, s3
	s_add_i32 m0, s31, 0x14000
	s_mul_i32 s11, s0, s52
	global_load_lds_dwordx4 v134, s[4:5]
	s_add_i32 m0, s31, 0x16000
	s_add_u32 s24, s26, s11
	v_mov_b32_e32 v135, v0
	v_mov_b32_e32 v139, v0
	s_addc_u32 s25, s27, s10
	s_add_i32 s34, s31, 0x2000
	v_mul_lo_u32 v18, v4, s6
	v_lshl_add_u64 v[6:7], s[4:5], 0, v[134:135]
	v_lshl_add_u64 v[8:9], s[4:5], 0, v[138:139]
	global_load_lds_dwordx4 v138, s[4:5]
	s_mov_b32 m0, s31
	s_add_u32 s4, s24, s2
	v_add_lshl_u32 v136, v2, v18, 1
	global_load_lds_dwordx4 v132, s[24:25]
	s_mov_b32 m0, s34
	s_addc_u32 s5, s25, s3
	s_add_i32 s35, s31, 0x4000
	global_load_lds_dwordx4 v136, s[24:25]
	s_mov_b32 m0, s35
	s_add_i32 s36, s31, 0x6000
	global_load_lds_dwordx4 v132, s[4:5]
	s_mov_b32 m0, s36
	v_mov_b32_e32 v133, v0
	global_load_lds_dwordx4 v136, s[4:5]
	v_mov_b32_e32 v137, v0
	s_cmp_eq_u32 s14, 1
	v_lshl_add_u64 v[2:3], s[18:19], 0, v[134:135]
	v_lshl_add_u64 v[4:5], s[18:19], 0, v[138:139]
	v_lshl_add_u64 v[10:11], s[24:25], 0, v[132:133]
	v_lshl_add_u64 v[12:13], s[24:25], 0, v[136:137]
	s_cselect_b64 s[4:5], -1, 0
	s_cmp_lg_u32 s14, 1
	s_cbranch_scc1 .LBB0_1026
	s_barrier

; #define GAS __attribute__((address_space(1)))
; __device__ __forceinline__ u32x4 pack8(f32x4 a, f32x4 b) { u32x4 w; w.x = cvtpk(a[0], a[1]); w.y = cvtpk(a[2], a[3]); w.z = cvtpk(b[0], b[1]); w.w = cvtpk(b[2], b[3]); return w; }
;     static __device__ __forceinline__ float gb(unsigned w, int sh) { return (float)max((w >> sh) & 0xffu, 1u); }
;     __device__ __forceinline__ void chain(f32x4 (&acc)[2][2][4][2], const pg8::Unit& u, bool has_next, int wr, int wc, int fr, int fq) const {
;     ...
; #pragma unroll
;             for (int h2 = 0; h2 < 2; ++h2) {
;                 u32x2 ga[8];
; #pragma unroll
;                 for (int m = 0; m < 4; ++m)
; #pragma unroll
;                     for (int bj = 0; bj < 2; ++bj) ga[2 * m + bj] = *(const GAS u32x2*)(ga_p + (h2 * 128 + m * 16) * 256 + bj * 128);
; #pragma unroll
;                 for (int m = 0; m < 4; ++m)
; #pragma unroll
;                     for (int bj = 0; bj < 2; ++bj) {
;                         const u32x2 a = ga[2 * m + bj]; const float k = 1.f / 255.f;
;                         f32x4 v0 = acc[h2][bj][m][0], v1 = acc[h2][bj][m][1];
;                         v0[0] *= gb(a.x, 0) * k; v0[1] *= gb(a.x, 8) * k; v0[2] *= gb(a.x, 16) * k; v0[3] *= gb(a.x, 24) * k;
;                         v1[0] *= gb(a.y, 0) * k; v1[1] *= gb(a.y, 8) * k; v1[2] *= gb(a.y, 16) * k; v1[3] *= gb(a.y, 24) * k;
;                         const int row = ro + wr * 64 + fr + h2 * 128 + m * 16, col = co + wc * 32 + 8 * fq + bj * 128;
;                         *(GAS u32x4*)(MG + (size_t)row * DM + col) = pack8(v0, v1);
;                     }
;             }
.LBB0_1041:
	global_load_dwordx2 v[176:177], v[2:3], off sc1
	global_load_dwordx2 v[174:175], v[2:3], off offset:128 sc1
	v_add_co_u32_e32 v162, vcc, 0x1000, v2
	s_nop 1
	v_addc_co_u32_e32 v163, vcc, 0, v3, vcc
	global_load_dwordx2 v[172:173], v[162:163], off sc1
	global_load_dwordx2 v[170:171], v[162:163], off offset:128 sc1
	v_add_co_u32_e32 v162, vcc, 0x2000, v2
	s_waitcnt vmcnt(0)
	v_lshrrev_b32_e32 v1, 8, v176
	v_addc_co_u32_e32 v163, vcc, 0, v3, vcc
	global_load_dwordx2 v[168:169], v[162:163], off sc1
	global_load_dwordx2 v[166:167], v[162:163], off offset:128 sc1
	v_add_co_u32_e32 v162, vcc, 0x3000, v2
	v_max_u32_sdwa v1, v1, v223 dst_sel:DWORD dst_unused:UNUSED_PAD src0_sel:BYTE_0 src1_sel:DWORD
	s_nop 0
	v_addc_co_u32_e32 v163, vcc, 0, v3, vcc
	global_load_dwordx2 v[164:165], v[162:163], off sc1
	s_nop 0
	global_load_dwordx2 v[162:163], v[162:163], off offset:128 sc1
	v_cvt_f32_ubyte0_e32 v179, v1
	v_max_u32_sdwa v1, v176, v223 dst_sel:DWORD dst_unused:UNUSED_PAD src0_sel:BYTE_2 src1_sel:DWORD
	v_max_u32_sdwa v178, v176, v223 dst_sel:DWORD dst_unused:UNUSED_PAD src0_sel:BYTE_0 src1_sel:DWORD
	v_max_u32_sdwa v176, v176, v223 dst_sel:DWORD dst_unused:UNUSED_PAD src0_sel:BYTE_3 src1_sel:DWORD
	v_cvt_f32_ubyte0_e32 v180, v1
	v_lshrrev_b32_e32 v1, 8, v177
	v_cvt_f32_ubyte0_e32 v181, v176
	v_max_u32_sdwa v176, v177, v223 dst_sel:DWORD dst_unused:UNUSED_PAD src0_sel:BYTE_0 src1_sel:DWORD
	v_max_u32_sdwa v1, v1, v223 dst_sel:DWORD dst_unused:UNUSED_PAD src0_sel:BYTE_0 src1_sel:DWORD
	v_cvt_f32_ubyte0_e32 v183, v1
	v_cvt_f32_ubyte0_e32 v182, v176
	v_max_u32_sdwa v1, v177, v223 dst_sel:DWORD dst_unused:UNUSED_PAD src0_sel:BYTE_2 src1_sel:DWORD
	v_max_u32_sdwa v176, v177, v223 dst_sel:DWORD dst_unused:UNUSED_PAD src0_sel:BYTE_3 src1_sel:DWORD
	v_cvt_f32_ubyte0_e32 v178, v178
	v_cvt_f32_ubyte0_e32 v177, v176
	v_cvt_f32_ubyte0_e32 v176, v1
	v_pk_mul_f32 v[178:179], v[178:179], s[22:23] op_sel_hi:[1,0]
	v_pk_mul_f32 v[180:181], v[180:181], s[22:23] op_sel_hi:[1,0]
	v_pk_mul_f32 v[182:183], v[182:183], s[22:23] op_sel_hi:[1,0]
	v_pk_mul_f32 v[176:177], v[176:177], s[22:23] op_sel_hi:[1,0]
	v_pk_mul_f32 v[178:179], v[128:129], v[178:179]
	v_pk_mul_f32 v[180:181], v[130:131], v[180:181]
	v_pk_mul_f32 v[182:183], v[124:125], v[182:183]
	v_pk_mul_f32 v[184:185], v[126:127], v[176:177]
	v_lshrrev_b32_e32 v1, 8, v174
	v_cvt_pk_bf16_f32 v176, v178, v179
	v_cvt_pk_bf16_f32 v177, v180, v181
	v_cvt_pk_bf16_f32 v178, v182, v183
	v_cvt_pk_bf16_f32 v179, v184, v185
	v_max_u32_sdwa v1, v1, v223 dst_sel:DWORD dst_unused:UNUSED_PAD src0_sel:BYTE_0 src1_sel:DWORD
	global_store_dwordx4 v[142:143], v[176:179], off
	s_nop 1
	v_cvt_f32_ubyte0_e32 v177, v1
	v_max_u32_sdwa v1, v174, v223 dst_sel:DWORD dst_unused:UNUSED_PAD src0_sel:BYTE_2 src1_sel:DWORD
	v_max_u32_sdwa v176, v174, v223 dst_sel:DWORD dst_unused:UNUSED_PAD src0_sel:BYTE_0 src1_sel:DWORD
	v_max_u32_sdwa v174, v174, v223 dst_sel:DWORD dst_unused:UNUSED_PAD src0_sel:BYTE_3 src1_sel:DWORD
	v_cvt_f32_ubyte0_e32 v178, v1
	v_lshrrev_b32_e32 v1, 8, v175
	v_cvt_f32_ubyte0_e32 v179, v174
	v_max_u32_sdwa v174, v175, v223 dst_sel:DWORD dst_unused:UNUSED_PAD src0_sel:BYTE_0 src1_sel:DWORD
	v_max_u32_sdwa v1, v1, v223 dst_sel:DWORD dst_unused:UNUSED_PAD src0_sel:BYTE_0 src1_sel:DWORD
	v_cvt_f32_ubyte0_e32 v181, v1
	v_cvt_f32_ubyte0_e32 v180, v174
	v_max_u32_sdwa v1, v175, v223 dst_sel:DWORD dst_unused:UNUSED_PAD src0_sel:BYTE_2 src1_sel:DWORD
	v_max_u32_sdwa v174, v175, v223 dst_sel:DWORD dst_unused:UNUSED_PAD src0_sel:BYTE_3 src1_sel:DWORD
	v_cvt_f32_ubyte0_e32 v176, v176
	v_cvt_f32_ubyte0_e32 v175, v174
	v_cvt_f32_ubyte0_e32 v174, v1
	v_pk_mul_f32 v[176:177], v[176:177], s[22:23] op_sel_hi:[1,0]
	v_pk_mul_f32 v[178:179], v[178:179], s[22:23] op_sel_hi:[1,0]
	v_pk_mul_f32 v[180:181], v[180:181], s[22:23] op_sel_hi:[1,0]
	v_pk_mul_f32 v[174:175], v[174:175], s[22:23] op_sel_hi:[1,0]
	v_pk_mul_f32 v[176:177], v[96:97], v[176:177]
	v_pk_mul_f32 v[178:179], v[98:99], v[178:179]
	v_pk_mul_f32 v[180:181], v[92:93], v[180:181]
	v_pk_mul_f32 v[182:183], v[94:95], v[174:175]
	v_lshrrev_b32_e32 v1, 8, v172
	v_cvt_pk_bf16_f32 v174, v176, v177
	v_cvt_pk_bf16_f32 v175, v178, v179
	v_cvt_pk_bf16_f32 v176, v180, v181
	v_cvt_pk_bf16_f32 v177, v182, v183
	v_max_u32_sdwa v1, v1, v223 dst_sel:DWORD dst_unused:UNUSED_PAD src0_sel:BYTE_0 src1_sel:DWORD
	global_store_dwordx4 v[142:143], v[174:177], off offset:256
	s_nop 1
	v_cvt_f32_ubyte0_e32 v175, v1
	v_max_u32_sdwa v1, v172, v223 dst_sel:DWORD dst_unused:UNUSED_PAD src0_sel:BYTE_2 src1_sel:DWORD
	v_max_u32_sdwa v174, v172, v223 dst_sel:DWORD dst_unused:UNUSED_PAD src0_sel:BYTE_0 src1_sel:DWORD
	v_max_u32_sdwa v172, v172, v223 dst_sel:DWORD dst_unused:UNUSED_PAD src0_sel:BYTE_3 src1_sel:DWORD
	v_cvt_f32_ubyte0_e32 v176, v1
	v_lshrrev_b32_e32 v1, 8, v173
	v_cvt_f32_ubyte0_e32 v177, v172
	v_max_u32_sdwa v172, v173, v223 dst_sel:DWORD dst_unused:UNUSED_PAD src0_sel:BYTE_0 src1_sel:DWORD
	v_max_u32_sdwa v1, v1, v223 dst_sel:DWORD dst_unused:UNUSED_PAD src0_sel:BYTE_0 src1_sel:DWORD
	v_cvt_f32_ubyte0_e32 v179, v1
	v_cvt_f32_ubyte0_e32 v178, v172
	v_max_u32_sdwa v1, v173, v223 dst_sel:DWORD dst_unused:UNUSED_PAD src0_sel:BYTE_2 src1_sel:DWORD
	v_max_u32_sdwa v172, v173, v223 dst_sel:DWORD dst_unused:UNUSED_PAD src0_sel:BYTE_3 src1_sel:DWORD
	v_cvt_f32_ubyte0_e32 v174, v174
	v_cvt_f32_ubyte0_e32 v173, v172
	v_cvt_f32_ubyte0_e32 v172, v1
	v_pk_mul_f32 v[174:175], v[174:175], s[22:23] op_sel_hi:[1,0]
	v_pk_mul_f32 v[176:177], v[176:177], s[22:23] op_sel_hi:[1,0]
	v_pk_mul_f32 v[178:179], v[178:179], s[22:23] op_sel_hi:[1,0]
	v_pk_mul_f32 v[172:173], v[172:173], s[22:23] op_sel_hi:[1,0]
; #define GAS __attribute__((address_space(1)))
; __device__ __forceinline__ u32x4 pack8(f32x4 a, f32x4 b) { u32x4 w; w.x = cvtpk(a[0], a[1]); w.y = cvtpk(a[2], a[3]); w.z = cvtpk(b[0], b[1]); w.w = cvtpk(b[2], b[3]); return w; }
;     static __device__ __forceinline__ float gb(unsigned w, int sh) { return (float)max((w >> sh) & 0xffu, 1u); }
;     __device__ __forceinline__ void chain(f32x4 (&acc)[2][2][4][2], const pg8::Unit& u, bool has_next, int wr, int wc, int fr, int fq) const {
;     ...
;                 for (int m = 0; m < 4; ++m)
; #pragma unroll
;                     for (int bj = 0; bj < 2; ++bj) {
;                         const u32x2 a = ga[2 * m + bj]; const float k = 1.f / 255.f;
;                         f32x4 v0 = acc[h2][bj][m][0], v1 = acc[h2][bj][m][1];
;                         v0[0] *= gb(a.x, 0) * k; v0[1] *= gb(a.x, 8) * k; v0[2] *= gb(a.x, 16) * k; v0[3] *= gb(a.x, 24) * k;
;                         v1[0] *= gb(a.y, 0) * k; v1[1] *= gb(a.y, 8) * k; v1[2] *= gb(a.y, 16) * k; v1[3] *= gb(a.y, 24) * k;
;                         const int row = ro + wr * 64 + fr + h2 * 128 + m * 16, col = co + wc * 32 + 8 * fq + bj * 128;
;                         *(GAS u32x4*)(MG + (size_t)row * DM + col) = pack8(v0, v1);
;                     }
	v_pk_mul_f32 v[174:175], v[120:121], v[174:175]
	v_pk_mul_f32 v[176:177], v[122:123], v[176:177]
	v_pk_mul_f32 v[178:179], v[116:117], v[178:179]
	v_pk_mul_f32 v[180:181], v[118:119], v[172:173]
	v_lshrrev_b32_e32 v1, 8, v170
	v_cvt_pk_bf16_f32 v172, v174, v175
	v_cvt_pk_bf16_f32 v173, v176, v177
	v_cvt_pk_bf16_f32 v174, v178, v179
	v_cvt_pk_bf16_f32 v175, v180, v181
	v_max_u32_sdwa v1, v1, v223 dst_sel:DWORD dst_unused:UNUSED_PAD src0_sel:BYTE_0 src1_sel:DWORD
	global_store_dwordx4 v[144:145], v[172:175], off
	s_nop 1
	v_cvt_f32_ubyte0_e32 v173, v1
	v_max_u32_sdwa v1, v170, v223 dst_sel:DWORD dst_unused:UNUSED_PAD src0_sel:BYTE_2 src1_sel:DWORD
	v_max_u32_sdwa v172, v170, v223 dst_sel:DWORD dst_unused:UNUSED_PAD src0_sel:BYTE_0 src1_sel:DWORD
	v_max_u32_sdwa v170, v170, v223 dst_sel:DWORD dst_unused:UNUSED_PAD src0_sel:BYTE_3 src1_sel:DWORD
	v_cvt_f32_ubyte0_e32 v174, v1
	v_lshrrev_b32_e32 v1, 8, v171
	v_cvt_f32_ubyte0_e32 v175, v170
	v_max_u32_sdwa v170, v171, v223 dst_sel:DWORD dst_unused:UNUSED_PAD src0_sel:BYTE_0 src1_sel:DWORD
	v_max_u32_sdwa v1, v1, v223 dst_sel:DWORD dst_unused:UNUSED_PAD src0_sel:BYTE_0 src1_sel:DWORD
	v_cvt_f32_ubyte0_e32 v177, v1
	v_cvt_f32_ubyte0_e32 v176, v170
	v_max_u32_sdwa v1, v171, v223 dst_sel:DWORD dst_unused:UNUSED_PAD src0_sel:BYTE_2 src1_sel:DWORD
	v_max_u32_sdwa v170, v171, v223 dst_sel:DWORD dst_unused:UNUSED_PAD src0_sel:BYTE_3 src1_sel:DWORD
	v_cvt_f32_ubyte0_e32 v172, v172
	v_cvt_f32_ubyte0_e32 v171, v170
	v_cvt_f32_ubyte0_e32 v170, v1
	v_pk_mul_f32 v[172:173], v[172:173], s[22:23] op_sel_hi:[1,0]
	v_pk_mul_f32 v[174:175], v[174:175], s[22:23] op_sel_hi:[1,0]
	v_pk_mul_f32 v[176:177], v[176:177], s[22:23] op_sel_hi:[1,0]
	v_pk_mul_f32 v[170:171], v[170:171], s[22:23] op_sel_hi:[1,0]
	v_pk_mul_f32 v[172:173], v[88:89], v[172:173]
	v_pk_mul_f32 v[174:175], v[90:91], v[174:175]
	v_pk_mul_f32 v[176:177], v[84:85], v[176:177]
	v_pk_mul_f32 v[178:179], v[86:87], v[170:171]
	s_waitcnt vmcnt(0)
	v_lshrrev_b32_e32 v1, 8, v168
	v_cvt_pk_bf16_f32 v170, v172, v173
	v_cvt_pk_bf16_f32 v171, v174, v175
	v_cvt_pk_bf16_f32 v172, v176, v177
	v_cvt_pk_bf16_f32 v173, v178, v179
	v_max_u32_sdwa v1, v1, v223 dst_sel:DWORD dst_unused:UNUSED_PAD src0_sel:BYTE_0 src1_sel:DWORD
	global_store_dwordx4 v[144:145], v[170:173], off offset:256
	s_nop 1
	v_cvt_f32_ubyte0_e32 v171, v1
	v_max_u32_sdwa v1, v168, v223 dst_sel:DWORD dst_unused:UNUSED_PAD src0_sel:BYTE_2 src1_sel:DWORD
	v_max_u32_sdwa v170, v168, v223 dst_sel:DWORD dst_unused:UNUSED_PAD src0_sel:BYTE_0 src1_sel:DWORD
	v_max_u32_sdwa v168, v168, v223 dst_sel:DWORD dst_unused:UNUSED_PAD src0_sel:BYTE_3 src1_sel:DWORD
	v_cvt_f32_ubyte0_e32 v172, v1
	v_lshrrev_b32_e32 v1, 8, v169
	v_cvt_f32_ubyte0_e32 v173, v168
	v_max_u32_sdwa v168, v169, v223 dst_sel:DWORD dst_unused:UNUSED_PAD src0_sel:BYTE_0 src1_sel:DWORD
	v_max_u32_sdwa v1, v1, v223 dst_sel:DWORD dst_unused:UNUSED_PAD src0_sel:BYTE_0 src1_sel:DWORD
	v_cvt_f32_ubyte0_e32 v175, v1
	v_cvt_f32_ubyte0_e32 v174, v168
	v_max_u32_sdwa v1, v169, v223 dst_sel:DWORD dst_unused:UNUSED_PAD src0_sel:BYTE_2 src1_sel:DWORD
	v_max_u32_sdwa v168, v169, v223 dst_sel:DWORD dst_unused:UNUSED_PAD src0_sel:BYTE_3 src1_sel:DWORD
	v_cvt_f32_ubyte0_e32 v170, v170
	v_cvt_f32_ubyte0_e32 v169, v168
	v_cvt_f32_ubyte0_e32 v168, v1
	v_pk_mul_f32 v[170:171], v[170:171], s[22:23] op_sel_hi:[1,0]
	v_pk_mul_f32 v[172:173], v[172:173], s[22:23] op_sel_hi:[1,0]
	v_pk_mul_f32 v[174:175], v[174:175], s[22:23] op_sel_hi:[1,0]
	v_pk_mul_f32 v[168:169], v[168:169], s[22:23] op_sel_hi:[1,0]
	v_pk_mul_f32 v[170:171], v[112:113], v[170:171]
	v_pk_mul_f32 v[172:173], v[114:115], v[172:173]
	v_pk_mul_f32 v[174:175], v[108:109], v[174:175]
	v_pk_mul_f32 v[176:177], v[110:111], v[168:169]
	v_lshrrev_b32_e32 v1, 8, v166
	v_cvt_pk_bf16_f32 v168, v170, v171
	v_cvt_pk_bf16_f32 v169, v172, v173
	v_cvt_pk_bf16_f32 v170, v174, v175
	v_cvt_pk_bf16_f32 v171, v176, v177
	v_max_u32_sdwa v1, v1, v223 dst_sel:DWORD dst_unused:UNUSED_PAD src0_sel:BYTE_0 src1_sel:DWORD
	global_store_dwordx4 v[146:147], v[168:171], off
	s_nop 1
	v_cvt_f32_ubyte0_e32 v169, v1
	v_max_u32_sdwa v1, v166, v223 dst_sel:DWORD dst_unused:UNUSED_PAD src0_sel:BYTE_2 src1_sel:DWORD
	v_max_u32_sdwa v168, v166, v223 dst_sel:DWORD dst_unused:UNUSED_PAD src0_sel:BYTE_0 src1_sel:DWORD
	v_max_u32_sdwa v166, v166, v223 dst_sel:DWORD dst_unused:UNUSED_PAD src0_sel:BYTE_3 src1_sel:DWORD
	v_cvt_f32_ubyte0_e32 v170, v1
	v_lshrrev_b32_e32 v1, 8, v167
	v_cvt_f32_ubyte0_e32 v171, v166
	v_max_u32_sdwa v166, v167, v223 dst_sel:DWORD dst_unused:UNUSED_PAD src0_sel:BYTE_0 src1_sel:DWORD
	v_max_u32_sdwa v1, v1, v223 dst_sel:DWORD dst_unused:UNUSED_PAD src0_sel:BYTE_0 src1_sel:DWORD
	v_cvt_f32_ubyte0_e32 v173, v1
	v_cvt_f32_ubyte0_e32 v172, v166
	v_max_u32_sdwa v1, v167, v223 dst_sel:DWORD dst_unused:UNUSED_PAD src0_sel:BYTE_2 src1_sel:DWORD
	v_max_u32_sdwa v166, v167, v223 dst_sel:DWORD dst_unused:UNUSED_PAD src0_sel:BYTE_3 src1_sel:DWORD
	v_cvt_f32_ubyte0_e32 v168, v168
	v_cvt_f32_ubyte0_e32 v167, v166
	v_cvt_f32_ubyte0_e32 v166, v1
	v_pk_mul_f32 v[168:169], v[168:169], s[22:23] op_sel_hi:[1,0]
	v_pk_mul_f32 v[170:171], v[170:171], s[22:23] op_sel_hi:[1,0]
	v_pk_mul_f32 v[172:173], v[172:173], s[22:23] op_sel_hi:[1,0]
	v_pk_mul_f32 v[166:167], v[166:167], s[22:23] op_sel_hi:[1,0]
	v_pk_mul_f32 v[168:169], v[80:81], v[168:169]
	v_pk_mul_f32 v[170:171], v[82:83], v[170:171]
	v_pk_mul_f32 v[172:173], v[76:77], v[172:173]
	v_pk_mul_f32 v[174:175], v[78:79], v[166:167]
	v_lshrrev_b32_e32 v1, 8, v164
	v_cvt_pk_bf16_f32 v166, v168, v169
	v_cvt_pk_bf16_f32 v167, v170, v171
	v_cvt_pk_bf16_f32 v168, v172, v173
	v_cvt_pk_bf16_f32 v169, v174, v175
; #define GAS __attribute__((address_space(1)))
; __device__ __forceinline__ u32x4 pack8(f32x4 a, f32x4 b) { u32x4 w; w.x = cvtpk(a[0], a[1]); w.y = cvtpk(a[2], a[3]); w.z = cvtpk(b[0], b[1]); w.w = cvtpk(b[2], b[3]); return w; }
;     static __device__ __forceinline__ float gb(unsigned w, int sh) { return (float)max((w >> sh) & 0xffu, 1u); }
;     __device__ __forceinline__ void chain(f32x4 (&acc)[2][2][4][2], const pg8::Unit& u, bool has_next, int wr, int wc, int fr, int fq) const {
;     ...
;             for (int h2 = 0; h2 < 2; ++h2) {
;                 u32x2 ga[8];
; #pragma unroll
;                 for (int m = 0; m < 4; ++m)
; #pragma unroll
;                     for (int bj = 0; bj < 2; ++bj) ga[2 * m + bj] = *(const GAS u32x2*)(ga_p + (h2 * 128 + m * 16) * 256 + bj * 128);
; #pragma unroll
;                 for (int m = 0; m < 4; ++m)
; #pragma unroll
;                     for (int bj = 0; bj < 2; ++bj) {
;                         const u32x2 a = ga[2 * m + bj]; const float k = 1.f / 255.f;
;                         f32x4 v0 = acc[h2][bj][m][0], v1 = acc[h2][bj][m][1];
;                         v0[0] *= gb(a.x, 0) * k; v0[1] *= gb(a.x, 8) * k; v0[2] *= gb(a.x, 16) * k; v0[3] *= gb(a.x, 24) * k;
;                         v1[0] *= gb(a.y, 0) * k; v1[1] *= gb(a.y, 8) * k; v1[2] *= gb(a.y, 16) * k; v1[3] *= gb(a.y, 24) * k;
;                         const int row = ro + wr * 64 + fr + h2 * 128 + m * 16, col = co + wc * 32 + 8 * fq + bj * 128;
;                         *(GAS u32x4*)(MG + (size_t)row * DM + col) = pack8(v0, v1);
;                     }
	v_max_u32_sdwa v1, v1, v223 dst_sel:DWORD dst_unused:UNUSED_PAD src0_sel:BYTE_0 src1_sel:DWORD
	global_store_dwordx4 v[146:147], v[166:169], off offset:256
	s_nop 1
	v_cvt_f32_ubyte0_e32 v167, v1
	v_max_u32_sdwa v1, v164, v223 dst_sel:DWORD dst_unused:UNUSED_PAD src0_sel:BYTE_2 src1_sel:DWORD
	v_max_u32_sdwa v166, v164, v223 dst_sel:DWORD dst_unused:UNUSED_PAD src0_sel:BYTE_0 src1_sel:DWORD
	v_max_u32_sdwa v164, v164, v223 dst_sel:DWORD dst_unused:UNUSED_PAD src0_sel:BYTE_3 src1_sel:DWORD
	v_cvt_f32_ubyte0_e32 v168, v1
	v_lshrrev_b32_e32 v1, 8, v165
	v_cvt_f32_ubyte0_e32 v169, v164
	v_max_u32_sdwa v164, v165, v223 dst_sel:DWORD dst_unused:UNUSED_PAD src0_sel:BYTE_0 src1_sel:DWORD
	v_max_u32_sdwa v1, v1, v223 dst_sel:DWORD dst_unused:UNUSED_PAD src0_sel:BYTE_0 src1_sel:DWORD
	v_cvt_f32_ubyte0_e32 v171, v1
	v_cvt_f32_ubyte0_e32 v170, v164
	v_max_u32_sdwa v1, v165, v223 dst_sel:DWORD dst_unused:UNUSED_PAD src0_sel:BYTE_2 src1_sel:DWORD
	v_max_u32_sdwa v164, v165, v223 dst_sel:DWORD dst_unused:UNUSED_PAD src0_sel:BYTE_3 src1_sel:DWORD
	v_cvt_f32_ubyte0_e32 v166, v166
	v_cvt_f32_ubyte0_e32 v165, v164
	v_cvt_f32_ubyte0_e32 v164, v1
	v_pk_mul_f32 v[166:167], v[166:167], s[22:23] op_sel_hi:[1,0]
	v_pk_mul_f32 v[168:169], v[168:169], s[22:23] op_sel_hi:[1,0]
	v_pk_mul_f32 v[170:171], v[170:171], s[22:23] op_sel_hi:[1,0]
	v_pk_mul_f32 v[164:165], v[164:165], s[22:23] op_sel_hi:[1,0]
	v_pk_mul_f32 v[166:167], v[104:105], v[166:167]
	v_pk_mul_f32 v[168:169], v[106:107], v[168:169]
	v_pk_mul_f32 v[170:171], v[100:101], v[170:171]
	v_pk_mul_f32 v[172:173], v[102:103], v[164:165]
	v_lshrrev_b32_e32 v1, 8, v162
	v_cvt_pk_bf16_f32 v164, v166, v167
	v_cvt_pk_bf16_f32 v165, v168, v169
	v_cvt_pk_bf16_f32 v166, v170, v171
	v_cvt_pk_bf16_f32 v167, v172, v173
	v_max_u32_sdwa v1, v1, v223 dst_sel:DWORD dst_unused:UNUSED_PAD src0_sel:BYTE_0 src1_sel:DWORD
	global_store_dwordx4 v[148:149], v[164:167], off
	s_nop 1
	v_cvt_f32_ubyte0_e32 v165, v1
	v_max_u32_sdwa v1, v162, v223 dst_sel:DWORD dst_unused:UNUSED_PAD src0_sel:BYTE_2 src1_sel:DWORD
	v_max_u32_sdwa v164, v162, v223 dst_sel:DWORD dst_unused:UNUSED_PAD src0_sel:BYTE_0 src1_sel:DWORD
	v_max_u32_sdwa v162, v162, v223 dst_sel:DWORD dst_unused:UNUSED_PAD src0_sel:BYTE_3 src1_sel:DWORD
	v_cvt_f32_ubyte0_e32 v166, v1
	v_lshrrev_b32_e32 v1, 8, v163
	v_cvt_f32_ubyte0_e32 v167, v162
	v_max_u32_sdwa v162, v163, v223 dst_sel:DWORD dst_unused:UNUSED_PAD src0_sel:BYTE_0 src1_sel:DWORD
	v_max_u32_sdwa v1, v1, v223 dst_sel:DWORD dst_unused:UNUSED_PAD src0_sel:BYTE_0 src1_sel:DWORD
	v_cvt_f32_ubyte0_e32 v169, v1
	v_cvt_f32_ubyte0_e32 v168, v162
	v_max_u32_sdwa v1, v163, v223 dst_sel:DWORD dst_unused:UNUSED_PAD src0_sel:BYTE_2 src1_sel:DWORD
	v_max_u32_sdwa v162, v163, v223 dst_sel:DWORD dst_unused:UNUSED_PAD src0_sel:BYTE_3 src1_sel:DWORD
	v_cvt_f32_ubyte0_e32 v164, v164
	v_cvt_f32_ubyte0_e32 v163, v162
	v_cvt_f32_ubyte0_e32 v162, v1
	v_pk_mul_f32 v[164:165], v[164:165], s[22:23] op_sel_hi:[1,0]
	v_pk_mul_f32 v[166:167], v[166:167], s[22:23] op_sel_hi:[1,0]
	v_pk_mul_f32 v[168:169], v[168:169], s[22:23] op_sel_hi:[1,0]
	v_pk_mul_f32 v[162:163], v[162:163], s[22:23] op_sel_hi:[1,0]
	v_pk_mul_f32 v[164:165], v[72:73], v[164:165]
	v_pk_mul_f32 v[166:167], v[74:75], v[166:167]
	v_pk_mul_f32 v[168:169], v[68:69], v[168:169]
	v_pk_mul_f32 v[170:171], v[70:71], v[162:163]
	v_cvt_pk_bf16_f32 v162, v164, v165
	v_cvt_pk_bf16_f32 v163, v166, v167
	v_cvt_pk_bf16_f32 v164, v168, v169
	v_cvt_pk_bf16_f32 v165, v170, v171
	global_store_dwordx4 v[148:149], v[162:165], off offset:256
	s_nop 1
	v_add_co_u32_e32 v162, vcc, s68, v2
	s_nop 1
	v_addc_co_u32_e32 v163, vcc, 0, v3, vcc
	v_add_co_u32_e32 v164, vcc, s69, v2
	s_nop 1
	v_addc_co_u32_e32 v165, vcc, 0, v3, vcc
	global_load_dwordx2 v[168:169], v[164:165], off offset:-4096 sc1
	global_load_dwordx2 v[172:173], v[162:163], off offset:128 sc1
	global_load_dwordx2 v[174:175], v[164:165], off sc1
	global_load_dwordx2 v[176:177], v[164:165], off offset:128 sc1
	v_add_co_u32_e32 v162, vcc, s62, v2
	s_waitcnt vmcnt(0)
	v_lshrrev_b32_e32 v1, 8, v168
	v_addc_co_u32_e32 v163, vcc, 0, v3, vcc
	v_add_co_u32_e32 v170, vcc, s63, v2
	v_max_u32_sdwa v1, v1, v223 dst_sel:DWORD dst_unused:UNUSED_PAD src0_sel:BYTE_0 src1_sel:DWORD
	s_nop 0
	v_addc_co_u32_e32 v171, vcc, 0, v3, vcc
	global_load_dwordx2 v[178:179], v[170:171], off offset:-4096 sc1
	global_load_dwordx2 v[166:167], v[162:163], off offset:128 sc1
	global_load_dwordx2 v[164:165], v[170:171], off sc1
	s_nop 0
	global_load_dwordx2 v[162:163], v[170:171], off offset:128 sc1
	v_cvt_f32_ubyte0_e32 v171, v1
	v_max_u32_sdwa v1, v168, v223 dst_sel:DWORD dst_unused:UNUSED_PAD src0_sel:BYTE_2 src1_sel:DWORD
	v_max_u32_sdwa v170, v168, v223 dst_sel:DWORD dst_unused:UNUSED_PAD src0_sel:BYTE_0 src1_sel:DWORD
	v_max_u32_sdwa v168, v168, v223 dst_sel:DWORD dst_unused:UNUSED_PAD src0_sel:BYTE_3 src1_sel:DWORD
	v_cvt_f32_ubyte0_e32 v180, v1
	v_lshrrev_b32_e32 v1, 8, v169
	v_cvt_f32_ubyte0_e32 v181, v168
	v_max_u32_sdwa v168, v169, v223 dst_sel:DWORD dst_unused:UNUSED_PAD src0_sel:BYTE_0 src1_sel:DWORD
	v_max_u32_sdwa v1, v1, v223 dst_sel:DWORD dst_unused:UNUSED_PAD src0_sel:BYTE_0 src1_sel:DWORD
	v_cvt_f32_ubyte0_e32 v183, v1
	v_cvt_f32_ubyte0_e32 v182, v168
	v_max_u32_sdwa v1, v169, v223 dst_sel:DWORD dst_unused:UNUSED_PAD src0_sel:BYTE_2 src1_sel:DWORD
	v_max_u32_sdwa v168, v169, v223 dst_sel:DWORD dst_unused:UNUSED_PAD src0_sel:BYTE_3 src1_sel:DWORD
	v_cvt_f32_ubyte0_e32 v170, v170
	v_cvt_f32_ubyte0_e32 v169, v168
	v_cvt_f32_ubyte0_e32 v168, v1
	v_pk_mul_f32 v[170:171], v[170:171], s[22:23] op_sel_hi:[1,0]
	v_pk_mul_f32 v[180:181], v[180:181], s[22:23] op_sel_hi:[1,0]
; #define GAS __attribute__((address_space(1)))
; __device__ __forceinline__ u32x4 pack8(f32x4 a, f32x4 b) { u32x4 w; w.x = cvtpk(a[0], a[1]); w.y = cvtpk(a[2], a[3]); w.z = cvtpk(b[0], b[1]); w.w = cvtpk(b[2], b[3]); return w; }
;     static __device__ __forceinline__ float gb(unsigned w, int sh) { return (float)max((w >> sh) & 0xffu, 1u); }
;     __device__ __forceinline__ void chain(f32x4 (&acc)[2][2][4][2], const pg8::Unit& u, bool has_next, int wr, int wc, int fr, int fq) const {
;     ...
;                 for (int m = 0; m < 4; ++m)
; #pragma unroll
;                     for (int bj = 0; bj < 2; ++bj) {
;                         const u32x2 a = ga[2 * m + bj]; const float k = 1.f / 255.f;
;                         f32x4 v0 = acc[h2][bj][m][0], v1 = acc[h2][bj][m][1];
;                         v0[0] *= gb(a.x, 0) * k; v0[1] *= gb(a.x, 8) * k; v0[2] *= gb(a.x, 16) * k; v0[3] *= gb(a.x, 24) * k;
;                         v1[0] *= gb(a.y, 0) * k; v1[1] *= gb(a.y, 8) * k; v1[2] *= gb(a.y, 16) * k; v1[3] *= gb(a.y, 24) * k;
;                         const int row = ro + wr * 64 + fr + h2 * 128 + m * 16, col = co + wc * 32 + 8 * fq + bj * 128;
;                         *(GAS u32x4*)(MG + (size_t)row * DM + col) = pack8(v0, v1);
;                     }
	v_pk_mul_f32 v[182:183], v[182:183], s[22:23] op_sel_hi:[1,0]
	v_pk_mul_f32 v[168:169], v[168:169], s[22:23] op_sel_hi:[1,0]
	v_pk_mul_f32 v[170:171], v[64:65], v[170:171]
	v_pk_mul_f32 v[180:181], v[66:67], v[180:181]
	v_pk_mul_f32 v[182:183], v[60:61], v[182:183]
	v_pk_mul_f32 v[184:185], v[62:63], v[168:169]
	v_lshrrev_b32_e32 v1, 8, v172
	v_cvt_pk_bf16_f32 v168, v170, v171
	v_cvt_pk_bf16_f32 v169, v180, v181
	v_cvt_pk_bf16_f32 v170, v182, v183
	v_cvt_pk_bf16_f32 v171, v184, v185
	v_max_u32_sdwa v1, v1, v223 dst_sel:DWORD dst_unused:UNUSED_PAD src0_sel:BYTE_0 src1_sel:DWORD
	global_store_dwordx4 v[150:151], v[168:171], off
	s_nop 1
	v_cvt_f32_ubyte0_e32 v169, v1
	v_max_u32_sdwa v1, v172, v223 dst_sel:DWORD dst_unused:UNUSED_PAD src0_sel:BYTE_2 src1_sel:DWORD
	v_max_u32_sdwa v170, v172, v223 dst_sel:DWORD dst_unused:UNUSED_PAD src0_sel:BYTE_3 src1_sel:DWORD
	v_cvt_f32_ubyte0_e32 v171, v170
	v_cvt_f32_ubyte0_e32 v170, v1
	v_lshrrev_b32_e32 v1, 8, v173
	v_max_u32_sdwa v168, v172, v223 dst_sel:DWORD dst_unused:UNUSED_PAD src0_sel:BYTE_0 src1_sel:DWORD
	v_max_u32_sdwa v172, v173, v223 dst_sel:DWORD dst_unused:UNUSED_PAD src0_sel:BYTE_0 src1_sel:DWORD
	v_max_u32_sdwa v1, v1, v223 dst_sel:DWORD dst_unused:UNUSED_PAD src0_sel:BYTE_0 src1_sel:DWORD
	v_cvt_f32_ubyte0_e32 v181, v1
	v_cvt_f32_ubyte0_e32 v180, v172
	v_max_u32_sdwa v1, v173, v223 dst_sel:DWORD dst_unused:UNUSED_PAD src0_sel:BYTE_2 src1_sel:DWORD
	v_max_u32_sdwa v172, v173, v223 dst_sel:DWORD dst_unused:UNUSED_PAD src0_sel:BYTE_3 src1_sel:DWORD
	v_cvt_f32_ubyte0_e32 v168, v168
	v_cvt_f32_ubyte0_e32 v173, v172
	v_cvt_f32_ubyte0_e32 v172, v1
	v_pk_mul_f32 v[168:169], v[168:169], s[22:23] op_sel_hi:[1,0]
	v_pk_mul_f32 v[170:171], v[170:171], s[22:23] op_sel_hi:[1,0]
	v_pk_mul_f32 v[180:181], v[180:181], s[22:23] op_sel_hi:[1,0]
	v_pk_mul_f32 v[172:173], v[172:173], s[22:23] op_sel_hi:[1,0]
	v_pk_mul_f32 v[168:169], v[32:33], v[168:169]
	v_pk_mul_f32 v[170:171], v[34:35], v[170:171]
	v_pk_mul_f32 v[180:181], v[28:29], v[180:181]
	v_pk_mul_f32 v[172:173], v[30:31], v[172:173]
	v_lshrrev_b32_e32 v1, 8, v174
	v_cvt_pk_bf16_f32 v168, v168, v169
	v_cvt_pk_bf16_f32 v169, v170, v171
	v_cvt_pk_bf16_f32 v170, v180, v181
	v_cvt_pk_bf16_f32 v171, v172, v173
	v_max_u32_sdwa v1, v1, v223 dst_sel:DWORD dst_unused:UNUSED_PAD src0_sel:BYTE_0 src1_sel:DWORD
	global_store_dwordx4 v[150:151], v[168:171], off offset:256
	v_max_u32_sdwa v172, v175, v223 dst_sel:DWORD dst_unused:UNUSED_PAD src0_sel:BYTE_0 src1_sel:DWORD
	v_cvt_f32_ubyte0_e32 v172, v172
	v_cvt_f32_ubyte0_e32 v169, v1
	v_max_u32_sdwa v1, v174, v223 dst_sel:DWORD dst_unused:UNUSED_PAD src0_sel:BYTE_2 src1_sel:DWORD
	v_max_u32_sdwa v170, v174, v223 dst_sel:DWORD dst_unused:UNUSED_PAD src0_sel:BYTE_3 src1_sel:DWORD
	v_cvt_f32_ubyte0_e32 v171, v170
	v_cvt_f32_ubyte0_e32 v170, v1
	v_lshrrev_b32_e32 v1, 8, v175
	v_max_u32_sdwa v1, v1, v223 dst_sel:DWORD dst_unused:UNUSED_PAD src0_sel:BYTE_0 src1_sel:DWORD
	v_max_u32_sdwa v168, v174, v223 dst_sel:DWORD dst_unused:UNUSED_PAD src0_sel:BYTE_0 src1_sel:DWORD
	v_cvt_f32_ubyte0_e32 v173, v1
	v_max_u32_sdwa v1, v175, v223 dst_sel:DWORD dst_unused:UNUSED_PAD src0_sel:BYTE_2 src1_sel:DWORD
	v_max_u32_sdwa v174, v175, v223 dst_sel:DWORD dst_unused:UNUSED_PAD src0_sel:BYTE_3 src1_sel:DWORD
	v_cvt_f32_ubyte0_e32 v168, v168
	v_cvt_f32_ubyte0_e32 v175, v174
	v_cvt_f32_ubyte0_e32 v174, v1
	v_pk_mul_f32 v[168:169], v[168:169], s[22:23] op_sel_hi:[1,0]
	v_pk_mul_f32 v[170:171], v[170:171], s[22:23] op_sel_hi:[1,0]
	v_pk_mul_f32 v[172:173], v[172:173], s[22:23] op_sel_hi:[1,0]
	v_pk_mul_f32 v[174:175], v[174:175], s[22:23] op_sel_hi:[1,0]
	v_pk_mul_f32 v[168:169], v[56:57], v[168:169]
	v_pk_mul_f32 v[170:171], v[58:59], v[170:171]
	v_pk_mul_f32 v[172:173], v[52:53], v[172:173]
	v_pk_mul_f32 v[174:175], v[54:55], v[174:175]
	v_lshrrev_b32_e32 v1, 8, v176
	v_cvt_pk_bf16_f32 v168, v168, v169
	v_cvt_pk_bf16_f32 v169, v170, v171
	v_cvt_pk_bf16_f32 v170, v172, v173
	v_cvt_pk_bf16_f32 v171, v174, v175
	v_max_u32_sdwa v1, v1, v223 dst_sel:DWORD dst_unused:UNUSED_PAD src0_sel:BYTE_0 src1_sel:DWORD
	global_store_dwordx4 v[152:153], v[168:171], off
	v_max_u32_sdwa v172, v177, v223 dst_sel:DWORD dst_unused:UNUSED_PAD src0_sel:BYTE_0 src1_sel:DWORD
	v_max_u32_sdwa v174, v177, v223 dst_sel:DWORD dst_unused:UNUSED_PAD src0_sel:BYTE_3 src1_sel:DWORD
	v_cvt_f32_ubyte0_e32 v169, v1
	v_max_u32_sdwa v1, v176, v223 dst_sel:DWORD dst_unused:UNUSED_PAD src0_sel:BYTE_2 src1_sel:DWORD
	v_max_u32_sdwa v170, v176, v223 dst_sel:DWORD dst_unused:UNUSED_PAD src0_sel:BYTE_3 src1_sel:DWORD
	v_cvt_f32_ubyte0_e32 v171, v170
	v_cvt_f32_ubyte0_e32 v170, v1
	v_lshrrev_b32_e32 v1, 8, v177
	v_max_u32_sdwa v1, v1, v223 dst_sel:DWORD dst_unused:UNUSED_PAD src0_sel:BYTE_0 src1_sel:DWORD
	v_max_u32_sdwa v168, v176, v223 dst_sel:DWORD dst_unused:UNUSED_PAD src0_sel:BYTE_0 src1_sel:DWORD
	v_cvt_f32_ubyte0_e32 v173, v1
	v_max_u32_sdwa v1, v177, v223 dst_sel:DWORD dst_unused:UNUSED_PAD src0_sel:BYTE_2 src1_sel:DWORD
	v_cvt_f32_ubyte0_e32 v168, v168
	v_cvt_f32_ubyte0_e32 v172, v172
	v_cvt_f32_ubyte0_e32 v175, v174
	v_cvt_f32_ubyte0_e32 v174, v1
	v_pk_mul_f32 v[168:169], v[168:169], s[22:23] op_sel_hi:[1,0]
	v_pk_mul_f32 v[170:171], v[170:171], s[22:23] op_sel_hi:[1,0]
	v_pk_mul_f32 v[172:173], v[172:173], s[22:23] op_sel_hi:[1,0]
	v_pk_mul_f32 v[174:175], v[174:175], s[22:23] op_sel_hi:[1,0]
	v_pk_mul_f32 v[168:169], v[24:25], v[168:169]
	v_pk_mul_f32 v[170:171], v[26:27], v[170:171]
	v_pk_mul_f32 v[172:173], v[20:21], v[172:173]
	v_pk_mul_f32 v[174:175], v[22:23], v[174:175]
	s_waitcnt vmcnt(0)
; #define GAS __attribute__((address_space(1)))
; __device__ __forceinline__ u32x4 pack8(f32x4 a, f32x4 b) { u32x4 w; w.x = cvtpk(a[0], a[1]); w.y = cvtpk(a[2], a[3]); w.z = cvtpk(b[0], b[1]); w.w = cvtpk(b[2], b[3]); return w; }
;     static __device__ __forceinline__ float gb(unsigned w, int sh) { return (float)max((w >> sh) & 0xffu, 1u); }
;     __device__ __forceinline__ void chain(f32x4 (&acc)[2][2][4][2], const pg8::Unit& u, bool has_next, int wr, int wc, int fr, int fq) const {
;     ...
;                 for (int m = 0; m < 4; ++m)
; #pragma unroll
;                     for (int bj = 0; bj < 2; ++bj) {
;                         const u32x2 a = ga[2 * m + bj]; const float k = 1.f / 255.f;
;                         f32x4 v0 = acc[h2][bj][m][0], v1 = acc[h2][bj][m][1];
;                         v0[0] *= gb(a.x, 0) * k; v0[1] *= gb(a.x, 8) * k; v0[2] *= gb(a.x, 16) * k; v0[3] *= gb(a.x, 24) * k;
;                         v1[0] *= gb(a.y, 0) * k; v1[1] *= gb(a.y, 8) * k; v1[2] *= gb(a.y, 16) * k; v1[3] *= gb(a.y, 24) * k;
;                         const int row = ro + wr * 64 + fr + h2 * 128 + m * 16, col = co + wc * 32 + 8 * fq + bj * 128;
;                         *(GAS u32x4*)(MG + (size_t)row * DM + col) = pack8(v0, v1);
;                     }
	v_lshrrev_b32_e32 v1, 8, v178
	v_cvt_pk_bf16_f32 v168, v168, v169
	v_cvt_pk_bf16_f32 v169, v170, v171
	v_cvt_pk_bf16_f32 v170, v172, v173
	v_cvt_pk_bf16_f32 v171, v174, v175
	v_max_u32_sdwa v1, v1, v223 dst_sel:DWORD dst_unused:UNUSED_PAD src0_sel:BYTE_0 src1_sel:DWORD
	global_store_dwordx4 v[152:153], v[168:171], off offset:256
	v_max_u32_sdwa v172, v179, v223 dst_sel:DWORD dst_unused:UNUSED_PAD src0_sel:BYTE_0 src1_sel:DWORD
	v_max_u32_sdwa v174, v179, v223 dst_sel:DWORD dst_unused:UNUSED_PAD src0_sel:BYTE_3 src1_sel:DWORD
	v_cvt_f32_ubyte0_e32 v169, v1
	v_max_u32_sdwa v1, v178, v223 dst_sel:DWORD dst_unused:UNUSED_PAD src0_sel:BYTE_2 src1_sel:DWORD
	v_max_u32_sdwa v170, v178, v223 dst_sel:DWORD dst_unused:UNUSED_PAD src0_sel:BYTE_3 src1_sel:DWORD
	v_cvt_f32_ubyte0_e32 v171, v170
	v_cvt_f32_ubyte0_e32 v170, v1
	v_lshrrev_b32_e32 v1, 8, v179
	v_max_u32_sdwa v1, v1, v223 dst_sel:DWORD dst_unused:UNUSED_PAD src0_sel:BYTE_0 src1_sel:DWORD
	v_max_u32_sdwa v168, v178, v223 dst_sel:DWORD dst_unused:UNUSED_PAD src0_sel:BYTE_0 src1_sel:DWORD
	v_cvt_f32_ubyte0_e32 v173, v1
	v_max_u32_sdwa v1, v179, v223 dst_sel:DWORD dst_unused:UNUSED_PAD src0_sel:BYTE_2 src1_sel:DWORD
	v_cvt_f32_ubyte0_e32 v168, v168
	v_cvt_f32_ubyte0_e32 v172, v172
	v_cvt_f32_ubyte0_e32 v175, v174
	v_cvt_f32_ubyte0_e32 v174, v1
	v_pk_mul_f32 v[168:169], v[168:169], s[22:23] op_sel_hi:[1,0]
	v_pk_mul_f32 v[170:171], v[170:171], s[22:23] op_sel_hi:[1,0]
	v_pk_mul_f32 v[172:173], v[172:173], s[22:23] op_sel_hi:[1,0]
	v_pk_mul_f32 v[174:175], v[174:175], s[22:23] op_sel_hi:[1,0]
	v_pk_mul_f32 v[168:169], v[48:49], v[168:169]
	v_pk_mul_f32 v[170:171], v[50:51], v[170:171]
	v_pk_mul_f32 v[172:173], v[44:45], v[172:173]
	v_pk_mul_f32 v[174:175], v[46:47], v[174:175]
	v_lshrrev_b32_e32 v1, 8, v166
	v_cvt_pk_bf16_f32 v168, v168, v169
	v_cvt_pk_bf16_f32 v169, v170, v171
	v_cvt_pk_bf16_f32 v170, v172, v173
	v_cvt_pk_bf16_f32 v171, v174, v175
	v_max_u32_sdwa v1, v1, v223 dst_sel:DWORD dst_unused:UNUSED_PAD src0_sel:BYTE_0 src1_sel:DWORD
	global_store_dwordx4 v[154:155], v[168:171], off
	s_nop 1
	v_cvt_f32_ubyte0_e32 v169, v1
	v_max_u32_sdwa v1, v166, v223 dst_sel:DWORD dst_unused:UNUSED_PAD src0_sel:BYTE_2 src1_sel:DWORD
	v_max_u32_sdwa v168, v166, v223 dst_sel:DWORD dst_unused:UNUSED_PAD src0_sel:BYTE_0 src1_sel:DWORD
	v_max_u32_sdwa v166, v166, v223 dst_sel:DWORD dst_unused:UNUSED_PAD src0_sel:BYTE_3 src1_sel:DWORD
	v_cvt_f32_ubyte0_e32 v170, v1
	v_lshrrev_b32_e32 v1, 8, v167
	v_cvt_f32_ubyte0_e32 v171, v166
	v_max_u32_sdwa v166, v167, v223 dst_sel:DWORD dst_unused:UNUSED_PAD src0_sel:BYTE_0 src1_sel:DWORD
	v_max_u32_sdwa v1, v1, v223 dst_sel:DWORD dst_unused:UNUSED_PAD src0_sel:BYTE_0 src1_sel:DWORD
	v_cvt_f32_ubyte0_e32 v173, v1
	v_cvt_f32_ubyte0_e32 v172, v166
	v_max_u32_sdwa v1, v167, v223 dst_sel:DWORD dst_unused:UNUSED_PAD src0_sel:BYTE_2 src1_sel:DWORD
	v_max_u32_sdwa v166, v167, v223 dst_sel:DWORD dst_unused:UNUSED_PAD src0_sel:BYTE_3 src1_sel:DWORD
	v_cvt_f32_ubyte0_e32 v168, v168
	v_cvt_f32_ubyte0_e32 v167, v166
	v_cvt_f32_ubyte0_e32 v166, v1
	v_pk_mul_f32 v[168:169], v[168:169], s[22:23] op_sel_hi:[1,0]
	v_pk_mul_f32 v[170:171], v[170:171], s[22:23] op_sel_hi:[1,0]
	v_pk_mul_f32 v[172:173], v[172:173], s[22:23] op_sel_hi:[1,0]
	v_pk_mul_f32 v[166:167], v[166:167], s[22:23] op_sel_hi:[1,0]
	v_pk_mul_f32 v[168:169], v[16:17], v[168:169]
	v_pk_mul_f32 v[170:171], v[18:19], v[170:171]
	v_pk_mul_f32 v[172:173], v[12:13], v[172:173]
	v_pk_mul_f32 v[174:175], v[14:15], v[166:167]
	v_lshrrev_b32_e32 v1, 8, v164
	v_cvt_pk_bf16_f32 v166, v168, v169
	v_cvt_pk_bf16_f32 v167, v170, v171
	v_cvt_pk_bf16_f32 v168, v172, v173
	v_cvt_pk_bf16_f32 v169, v174, v175
	v_max_u32_sdwa v1, v1, v223 dst_sel:DWORD dst_unused:UNUSED_PAD src0_sel:BYTE_0 src1_sel:DWORD
	global_store_dwordx4 v[154:155], v[166:169], off offset:256
	s_nop 1
	v_cvt_f32_ubyte0_e32 v167, v1
	v_max_u32_sdwa v1, v164, v223 dst_sel:DWORD dst_unused:UNUSED_PAD src0_sel:BYTE_2 src1_sel:DWORD
	v_max_u32_sdwa v166, v164, v223 dst_sel:DWORD dst_unused:UNUSED_PAD src0_sel:BYTE_0 src1_sel:DWORD
	v_max_u32_sdwa v164, v164, v223 dst_sel:DWORD dst_unused:UNUSED_PAD src0_sel:BYTE_3 src1_sel:DWORD
	v_cvt_f32_ubyte0_e32 v168, v1
	v_lshrrev_b32_e32 v1, 8, v165
	v_cvt_f32_ubyte0_e32 v169, v164
	v_max_u32_sdwa v164, v165, v223 dst_sel:DWORD dst_unused:UNUSED_PAD src0_sel:BYTE_0 src1_sel:DWORD
	v_max_u32_sdwa v1, v1, v223 dst_sel:DWORD dst_unused:UNUSED_PAD src0_sel:BYTE_0 src1_sel:DWORD
	v_cvt_f32_ubyte0_e32 v171, v1
	v_cvt_f32_ubyte0_e32 v170, v164
	v_max_u32_sdwa v1, v165, v223 dst_sel:DWORD dst_unused:UNUSED_PAD src0_sel:BYTE_2 src1_sel:DWORD
	v_max_u32_sdwa v164, v165, v223 dst_sel:DWORD dst_unused:UNUSED_PAD src0_sel:BYTE_3 src1_sel:DWORD
	v_cvt_f32_ubyte0_e32 v166, v166
	v_cvt_f32_ubyte0_e32 v165, v164
	v_cvt_f32_ubyte0_e32 v164, v1
	v_pk_mul_f32 v[166:167], v[166:167], s[22:23] op_sel_hi:[1,0]
	v_pk_mul_f32 v[168:169], v[168:169], s[22:23] op_sel_hi:[1,0]
	v_pk_mul_f32 v[170:171], v[170:171], s[22:23] op_sel_hi:[1,0]
	v_pk_mul_f32 v[164:165], v[164:165], s[22:23] op_sel_hi:[1,0]
	v_pk_mul_f32 v[166:167], v[40:41], v[166:167]
	v_pk_mul_f32 v[168:169], v[42:43], v[168:169]
	v_pk_mul_f32 v[170:171], v[36:37], v[170:171]
	v_pk_mul_f32 v[172:173], v[38:39], v[164:165]
	v_lshrrev_b32_e32 v1, 8, v162
	v_cvt_pk_bf16_f32 v164, v166, v167
	v_cvt_pk_bf16_f32 v165, v168, v169
	v_cvt_pk_bf16_f32 v166, v170, v171
	v_cvt_pk_bf16_f32 v167, v172, v173
	v_max_u32_sdwa v1, v1, v223 dst_sel:DWORD dst_unused:UNUSED_PAD src0_sel:BYTE_0 src1_sel:DWORD
	global_store_dwordx4 v[156:157], v[164:167], off
	s_nop 1
	v_cvt_f32_ubyte0_e32 v165, v1
; #define GAS __attribute__((address_space(1)))
;     static __device__ __forceinline__ float gb(unsigned w, int sh) { return (float)max((w >> sh) & 0xffu, 1u); }
;     __device__ __forceinline__ void chain(f32x4 (&acc)[2][2][4][2], const pg8::Unit& u, bool has_next, int wr, int wc, int fr, int fq) const {
;     ...
;         if (has_next) {
; #pragma unroll
;             for (int h2 = 0; h2 < 2; ++h2) {
;                 u32x2 ga[8], gn[8];
; #pragma unroll
;                 for (int m = 0; m < 4; ++m)
; #pragma unroll
;                     for (int bj = 0; bj < 2; ++bj) { const int o = (h2 * 128 + m * 16) * 256 + bj * 128; ga[2 * m + bj] = *(const GAS u32x2*)(ga_p + o); gn[2 * m + bj] = *(const GAS u32x2*)(ga_p + 65536 + o); }
; #pragma unroll
;                 for (int m = 0; m < 4; ++m)
; #pragma unroll
;                     for (int bj = 0; bj < 2; ++bj) {
;                         const u32x2 a = ga[2 * m + bj], n = gn[2 * m + bj];
;                         f32x4 v0 = acc[h2][bj][m][0], v1 = acc[h2][bj][m][1];
;                         v0[0] *= gb(a.x, 0) * __builtin_amdgcn_rcpf(gb(n.x, 0)); v0[1] *= gb(a.x, 8) * __builtin_amdgcn_rcpf(gb(n.x, 8));
;                         v0[2] *= gb(a.x, 16) * __builtin_amdgcn_rcpf(gb(n.x, 16)); v0[3] *= gb(a.x, 24) * __builtin_amdgcn_rcpf(gb(n.x, 24));
;                         v1[0] *= gb(a.y, 0) * __builtin_amdgcn_rcpf(gb(n.y, 0)); v1[1] *= gb(a.y, 8) * __builtin_amdgcn_rcpf(gb(n.y, 8));
;                         v1[2] *= gb(a.y, 16) * __builtin_amdgcn_rcpf(gb(n.y, 16)); v1[3] *= gb(a.y, 24) * __builtin_amdgcn_rcpf(gb(n.y, 24));
;                         acc[h2][bj][m][0] = v0; acc[h2][bj][m][1] = v1;
	v_max_u32_sdwa v1, v162, v223 dst_sel:DWORD dst_unused:UNUSED_PAD src0_sel:BYTE_2 src1_sel:DWORD
	v_max_u32_sdwa v164, v162, v223 dst_sel:DWORD dst_unused:UNUSED_PAD src0_sel:BYTE_0 src1_sel:DWORD
	v_max_u32_sdwa v162, v162, v223 dst_sel:DWORD dst_unused:UNUSED_PAD src0_sel:BYTE_3 src1_sel:DWORD
	v_cvt_f32_ubyte0_e32 v166, v1
	v_lshrrev_b32_e32 v1, 8, v163
	v_cvt_f32_ubyte0_e32 v167, v162
	v_max_u32_sdwa v162, v163, v223 dst_sel:DWORD dst_unused:UNUSED_PAD src0_sel:BYTE_0 src1_sel:DWORD
	v_max_u32_sdwa v1, v1, v223 dst_sel:DWORD dst_unused:UNUSED_PAD src0_sel:BYTE_0 src1_sel:DWORD
	v_cvt_f32_ubyte0_e32 v169, v1
	v_cvt_f32_ubyte0_e32 v168, v162
	v_max_u32_sdwa v1, v163, v223 dst_sel:DWORD dst_unused:UNUSED_PAD src0_sel:BYTE_2 src1_sel:DWORD
	v_max_u32_sdwa v162, v163, v223 dst_sel:DWORD dst_unused:UNUSED_PAD src0_sel:BYTE_3 src1_sel:DWORD
	v_cvt_f32_ubyte0_e32 v164, v164
	v_cvt_f32_ubyte0_e32 v163, v162
	v_cvt_f32_ubyte0_e32 v162, v1
	v_pk_mul_f32 v[164:165], v[164:165], s[22:23] op_sel_hi:[1,0]
	v_pk_mul_f32 v[166:167], v[166:167], s[22:23] op_sel_hi:[1,0]
	v_pk_mul_f32 v[168:169], v[168:169], s[22:23] op_sel_hi:[1,0]
	v_pk_mul_f32 v[162:163], v[162:163], s[22:23] op_sel_hi:[1,0]
	v_pk_mul_f32 v[164:165], v[8:9], v[164:165]
	v_pk_mul_f32 v[166:167], v[10:11], v[166:167]
	v_pk_mul_f32 v[168:169], v[4:5], v[168:169]
	v_pk_mul_f32 v[170:171], v[6:7], v[162:163]
	v_cvt_pk_bf16_f32 v162, v164, v165
	v_cvt_pk_bf16_f32 v163, v166, v167
	v_cvt_pk_bf16_f32 v164, v168, v169
	v_cvt_pk_bf16_f32 v165, v170, v171
	global_store_dwordx4 v[156:157], v[162:165], off offset:256
	s_cbranch_execnz .LBB0_1040
.LBB0_1042:
	s_nop 0
	v_add_co_u32_e32 v162, vcc, 0x10000, v2
	global_load_dwordx2 v[190:191], v[2:3], off sc1
	s_nop 0
	v_addc_co_u32_e32 v163, vcc, 0, v3, vcc
	global_load_dwordx2 v[192:193], v[162:163], off sc1
	global_load_dwordx2 v[186:187], v[2:3], off offset:128 sc1
	global_load_dwordx2 v[188:189], v[162:163], off offset:128 sc1
	v_add_co_u32_e32 v162, vcc, 0x1000, v2
	s_movk_i32 s16, 0x2000
	s_nop 0
	v_addc_co_u32_e32 v163, vcc, 0, v3, vcc
	v_add_co_u32_e32 v164, vcc, 0x11000, v2
	global_load_dwordx2 v[180:181], v[162:163], off sc1
	s_nop 0
	v_addc_co_u32_e32 v165, vcc, 0, v3, vcc
	global_load_dwordx2 v[184:185], v[164:165], off sc1
	global_load_dwordx2 v[168:169], v[162:163], off offset:128 sc1
	global_load_dwordx2 v[174:175], v[164:165], off offset:128 sc1
	v_add_co_u32_e32 v162, vcc, s16, v2
	s_movk_i32 s16, 0x3000
	s_nop 0
	v_addc_co_u32_e32 v163, vcc, 0, v3, vcc
	v_add_co_u32_e32 v164, vcc, s16, v2
	s_mov_b32 s16, 0x12000
	s_nop 0
	v_addc_co_u32_e32 v165, vcc, 0, v3, vcc
	v_add_co_u32_e32 v166, vcc, s16, v2
	global_load_dwordx2 v[170:171], v[164:165], off offset:-4096 sc1
	s_nop 0
	v_addc_co_u32_e32 v167, vcc, 0, v3, vcc
	s_mov_b32 s16, 0x13000
	v_add_co_u32_e32 v198, vcc, s16, v2
	s_mov_b32 s16, 0x19000
	s_nop 0
	v_addc_co_u32_e32 v199, vcc, 0, v3, vcc
	global_load_dwordx2 v[182:183], v[198:199], off offset:-4096 sc1
	global_load_dwordx2 v[176:177], v[162:163], off offset:128 sc1
	global_load_dwordx2 v[178:179], v[166:167], off offset:128 sc1
	s_nop 0
	global_load_dwordx2 v[166:167], v[164:165], off sc1
	global_load_dwordx2 v[172:173], v[198:199], off sc1
	global_load_dwordx2 v[162:163], v[164:165], off offset:128 sc1
	s_nop 0
	global_load_dwordx2 v[164:165], v[198:199], off offset:128 sc1
	s_waitcnt vmcnt(0)
	v_max_u32_sdwa v1, v192, v223 dst_sel:DWORD dst_unused:UNUSED_PAD src0_sel:BYTE_0 src1_sel:DWORD
	v_max_u32_sdwa v197, v192, v223 dst_sel:DWORD dst_unused:UNUSED_PAD src0_sel:BYTE_1 src1_sel:DWORD
	v_cvt_f32_ubyte0_e32 v1, v1
	v_cvt_f32_ubyte0_e32 v197, v197
	v_rcp_iflag_f32_e32 v198, v1
	v_rcp_iflag_f32_e32 v199, v197
	v_max_u32_sdwa v197, v192, v223 dst_sel:DWORD dst_unused:UNUSED_PAD src0_sel:BYTE_2 src1_sel:DWORD
	v_max_u32_sdwa v192, v192, v223 dst_sel:DWORD dst_unused:UNUSED_PAD src0_sel:BYTE_3 src1_sel:DWORD
	v_lshrrev_b32_e32 v1, 8, v190
	v_cvt_f32_ubyte0_e32 v197, v197
	v_cvt_f32_ubyte0_e32 v192, v192
	v_rcp_iflag_f32_e32 v200, v197
	v_rcp_iflag_f32_e32 v201, v192
	v_max_u32_sdwa v192, v190, v223 dst_sel:DWORD dst_unused:UNUSED_PAD src0_sel:BYTE_0 src1_sel:DWORD
	v_max_u32_sdwa v1, v1, v223 dst_sel:DWORD dst_unused:UNUSED_PAD src0_sel:BYTE_0 src1_sel:DWORD
	v_max_u32_sdwa v197, v190, v223 dst_sel:DWORD dst_unused:UNUSED_PAD src0_sel:BYTE_2 src1_sel:DWORD
	v_max_u32_sdwa v190, v190, v223 dst_sel:DWORD dst_unused:UNUSED_PAD src0_sel:BYTE_3 src1_sel:DWORD
	v_cvt_f32_ubyte0_e32 v203, v1
	v_cvt_f32_ubyte0_e32 v202, v192
	v_cvt_f32_ubyte0_e32 v205, v190
	v_max_u32_sdwa v190, v193, v223 dst_sel:DWORD dst_unused:UNUSED_PAD src0_sel:BYTE_1 src1_sel:DWORD
	v_pk_mul_f32 v[198:199], v[198:199], v[202:203]
	v_cvt_f32_ubyte0_e32 v190, v190
	v_pk_mul_f32 v[128:129], v[128:129], v[198:199]
	v_max_u32_sdwa v1, v193, v223 dst_sel:DWORD dst_unused:UNUSED_PAD src0_sel:BYTE_0 src1_sel:DWORD
	v_rcp_iflag_f32_e32 v199, v190
	v_max_u32_sdwa v190, v193, v223 dst_sel:DWORD dst_unused:UNUSED_PAD src0_sel:BYTE_2 src1_sel:DWORD
	v_cvt_f32_ubyte0_e32 v1, v1
	v_cvt_f32_ubyte0_e32 v190, v190
	v_rcp_iflag_f32_e32 v198, v1
	v_rcp_iflag_f32_e32 v192, v190
	v_max_u32_sdwa v190, v193, v223 dst_sel:DWORD dst_unused:UNUSED_PAD src0_sel:BYTE_3 src1_sel:DWORD
	v_cvt_f32_ubyte0_e32 v204, v197
	v_lshrrev_b32_e32 v1, 8, v191
	v_cvt_f32_ubyte0_e32 v190, v190
	v_pk_mul_f32 v[200:201], v[200:201], v[204:205]
	v_rcp_iflag_f32_e32 v193, v190
	v_max_u32_sdwa v190, v191, v223 dst_sel:DWORD dst_unused:UNUSED_PAD src0_sel:BYTE_0 src1_sel:DWORD
	v_max_u32_sdwa v1, v1, v223 dst_sel:DWORD dst_unused:UNUSED_PAD src0_sel:BYTE_0 src1_sel:DWORD
	v_pk_mul_f32 v[130:131], v[130:131], v[200:201]
;     static __device__ __forceinline__ float gb(unsigned w, int sh) { return (float)max((w >> sh) & 0xffu, 1u); }
;     __device__ __forceinline__ void chain(f32x4 (&acc)[2][2][4][2], const pg8::Unit& u, bool has_next, int wr, int wc, int fr, int fq) const {
;     ...
;                 for (int m = 0; m < 4; ++m)
; #pragma unroll
;                     for (int bj = 0; bj < 2; ++bj) {
;                         const u32x2 a = ga[2 * m + bj], n = gn[2 * m + bj];
;                         f32x4 v0 = acc[h2][bj][m][0], v1 = acc[h2][bj][m][1];
;                         v0[0] *= gb(a.x, 0) * __builtin_amdgcn_rcpf(gb(n.x, 0)); v0[1] *= gb(a.x, 8) * __builtin_amdgcn_rcpf(gb(n.x, 8));
;                         v0[2] *= gb(a.x, 16) * __builtin_amdgcn_rcpf(gb(n.x, 16)); v0[3] *= gb(a.x, 24) * __builtin_amdgcn_rcpf(gb(n.x, 24));
;                         v1[0] *= gb(a.y, 0) * __builtin_amdgcn_rcpf(gb(n.y, 0)); v1[1] *= gb(a.y, 8) * __builtin_amdgcn_rcpf(gb(n.y, 8));
;                         v1[2] *= gb(a.y, 16) * __builtin_amdgcn_rcpf(gb(n.y, 16)); v1[3] *= gb(a.y, 24) * __builtin_amdgcn_rcpf(gb(n.y, 24));
;                         acc[h2][bj][m][0] = v0; acc[h2][bj][m][1] = v1;
	v_max_u32_sdwa v197, v191, v223 dst_sel:DWORD dst_unused:UNUSED_PAD src0_sel:BYTE_2 src1_sel:DWORD
	v_max_u32_sdwa v200, v191, v223 dst_sel:DWORD dst_unused:UNUSED_PAD src0_sel:BYTE_3 src1_sel:DWORD
	v_cvt_f32_ubyte0_e32 v191, v1
	v_cvt_f32_ubyte0_e32 v190, v190
	v_pk_mul_f32 v[190:191], v[198:199], v[190:191]
	v_cvt_f32_ubyte0_e32 v201, v200
	v_cvt_f32_ubyte0_e32 v200, v197
	v_pk_mul_f32 v[124:125], v[124:125], v[190:191]
	v_max_u32_sdwa v1, v188, v223 dst_sel:DWORD dst_unused:UNUSED_PAD src0_sel:BYTE_0 src1_sel:DWORD
	v_max_u32_sdwa v191, v188, v223 dst_sel:DWORD dst_unused:UNUSED_PAD src0_sel:BYTE_1 src1_sel:DWORD
	v_pk_mul_f32 v[192:193], v[192:193], v[200:201]
	v_cvt_f32_ubyte0_e32 v1, v1
	v_cvt_f32_ubyte0_e32 v191, v191
	v_pk_mul_f32 v[126:127], v[126:127], v[192:193]
	v_rcp_iflag_f32_e32 v190, v1
	v_rcp_iflag_f32_e32 v191, v191
	v_max_u32_sdwa v192, v188, v223 dst_sel:DWORD dst_unused:UNUSED_PAD src0_sel:BYTE_2 src1_sel:DWORD
	v_max_u32_sdwa v188, v188, v223 dst_sel:DWORD dst_unused:UNUSED_PAD src0_sel:BYTE_3 src1_sel:DWORD
	v_lshrrev_b32_e32 v1, 8, v186
	v_cvt_f32_ubyte0_e32 v188, v188
	v_rcp_iflag_f32_e32 v193, v188
	v_max_u32_sdwa v188, v186, v223 dst_sel:DWORD dst_unused:UNUSED_PAD src0_sel:BYTE_0 src1_sel:DWORD
	v_max_u32_sdwa v1, v1, v223 dst_sel:DWORD dst_unused:UNUSED_PAD src0_sel:BYTE_0 src1_sel:DWORD
	v_max_u32_sdwa v197, v186, v223 dst_sel:DWORD dst_unused:UNUSED_PAD src0_sel:BYTE_2 src1_sel:DWORD
	v_max_u32_sdwa v186, v186, v223 dst_sel:DWORD dst_unused:UNUSED_PAD src0_sel:BYTE_3 src1_sel:DWORD
	v_cvt_f32_ubyte0_e32 v199, v1
	v_cvt_f32_ubyte0_e32 v198, v188
	v_cvt_f32_ubyte0_e32 v201, v186
	v_max_u32_sdwa v186, v189, v223 dst_sel:DWORD dst_unused:UNUSED_PAD src0_sel:BYTE_1 src1_sel:DWORD
	v_cvt_f32_ubyte0_e32 v192, v192
	v_pk_mul_f32 v[190:191], v[190:191], v[198:199]
	v_cvt_f32_ubyte0_e32 v186, v186
	v_rcp_iflag_f32_e32 v192, v192
	v_pk_mul_f32 v[96:97], v[96:97], v[190:191]
	v_max_u32_sdwa v1, v189, v223 dst_sel:DWORD dst_unused:UNUSED_PAD src0_sel:BYTE_0 src1_sel:DWORD
	v_rcp_iflag_f32_e32 v191, v186
	v_max_u32_sdwa v186, v189, v223 dst_sel:DWORD dst_unused:UNUSED_PAD src0_sel:BYTE_2 src1_sel:DWORD
	v_cvt_f32_ubyte0_e32 v1, v1
	v_cvt_f32_ubyte0_e32 v186, v186
	v_rcp_iflag_f32_e32 v190, v1
	v_rcp_iflag_f32_e32 v188, v186
	v_max_u32_sdwa v186, v189, v223 dst_sel:DWORD dst_unused:UNUSED_PAD src0_sel:BYTE_3 src1_sel:DWORD
	v_cvt_f32_ubyte0_e32 v200, v197
	v_lshrrev_b32_e32 v1, 8, v187
	v_cvt_f32_ubyte0_e32 v186, v186
	v_pk_mul_f32 v[192:193], v[192:193], v[200:201]
	v_rcp_iflag_f32_e32 v189, v186
	v_max_u32_sdwa v186, v187, v223 dst_sel:DWORD dst_unused:UNUSED_PAD src0_sel:BYTE_0 src1_sel:DWORD
	v_max_u32_sdwa v1, v1, v223 dst_sel:DWORD dst_unused:UNUSED_PAD src0_sel:BYTE_0 src1_sel:DWORD
	v_pk_mul_f32 v[98:99], v[98:99], v[192:193]
	v_max_u32_sdwa v192, v187, v223 dst_sel:DWORD dst_unused:UNUSED_PAD src0_sel:BYTE_2 src1_sel:DWORD
	v_max_u32_sdwa v193, v187, v223 dst_sel:DWORD dst_unused:UNUSED_PAD src0_sel:BYTE_3 src1_sel:DWORD
	v_cvt_f32_ubyte0_e32 v187, v1
	v_cvt_f32_ubyte0_e32 v186, v186
	v_pk_mul_f32 v[186:187], v[190:191], v[186:187]
	v_cvt_f32_ubyte0_e32 v193, v193
	v_cvt_f32_ubyte0_e32 v192, v192
	v_pk_mul_f32 v[92:93], v[92:93], v[186:187]
	v_max_u32_sdwa v1, v184, v223 dst_sel:DWORD dst_unused:UNUSED_PAD src0_sel:BYTE_0 src1_sel:DWORD
	v_max_u32_sdwa v187, v184, v223 dst_sel:DWORD dst_unused:UNUSED_PAD src0_sel:BYTE_1 src1_sel:DWORD
	v_pk_mul_f32 v[188:189], v[188:189], v[192:193]
	v_cvt_f32_ubyte0_e32 v1, v1
	v_cvt_f32_ubyte0_e32 v187, v187
	v_pk_mul_f32 v[94:95], v[94:95], v[188:189]
	v_rcp_iflag_f32_e32 v186, v1
	v_rcp_iflag_f32_e32 v187, v187
	v_max_u32_sdwa v188, v184, v223 dst_sel:DWORD dst_unused:UNUSED_PAD src0_sel:BYTE_2 src1_sel:DWORD
	v_max_u32_sdwa v184, v184, v223 dst_sel:DWORD dst_unused:UNUSED_PAD src0_sel:BYTE_3 src1_sel:DWORD
	v_lshrrev_b32_e32 v1, 8, v180
	v_cvt_f32_ubyte0_e32 v184, v184
	v_rcp_iflag_f32_e32 v189, v184
	v_max_u32_sdwa v184, v180, v223 dst_sel:DWORD dst_unused:UNUSED_PAD src0_sel:BYTE_0 src1_sel:DWORD
	v_max_u32_sdwa v1, v1, v223 dst_sel:DWORD dst_unused:UNUSED_PAD src0_sel:BYTE_0 src1_sel:DWORD
	v_max_u32_sdwa v192, v180, v223 dst_sel:DWORD dst_unused:UNUSED_PAD src0_sel:BYTE_2 src1_sel:DWORD
	v_max_u32_sdwa v180, v180, v223 dst_sel:DWORD dst_unused:UNUSED_PAD src0_sel:BYTE_3 src1_sel:DWORD
	v_cvt_f32_ubyte0_e32 v191, v1
	v_cvt_f32_ubyte0_e32 v190, v184
	v_cvt_f32_ubyte0_e32 v193, v180
	v_max_u32_sdwa v180, v185, v223 dst_sel:DWORD dst_unused:UNUSED_PAD src0_sel:BYTE_1 src1_sel:DWORD
	v_cvt_f32_ubyte0_e32 v188, v188
	v_pk_mul_f32 v[186:187], v[186:187], v[190:191]
	v_cvt_f32_ubyte0_e32 v180, v180
	v_rcp_iflag_f32_e32 v188, v188
	v_pk_mul_f32 v[120:121], v[120:121], v[186:187]
	v_max_u32_sdwa v1, v185, v223 dst_sel:DWORD dst_unused:UNUSED_PAD src0_sel:BYTE_0 src1_sel:DWORD
	v_rcp_iflag_f32_e32 v187, v180
	v_max_u32_sdwa v180, v185, v223 dst_sel:DWORD dst_unused:UNUSED_PAD src0_sel:BYTE_2 src1_sel:DWORD
	v_cvt_f32_ubyte0_e32 v1, v1
	v_cvt_f32_ubyte0_e32 v180, v180
	v_rcp_iflag_f32_e32 v186, v1
	v_rcp_iflag_f32_e32 v184, v180
	v_max_u32_sdwa v180, v185, v223 dst_sel:DWORD dst_unused:UNUSED_PAD src0_sel:BYTE_3 src1_sel:DWORD
	v_cvt_f32_ubyte0_e32 v192, v192
	v_lshrrev_b32_e32 v1, 8, v181
	v_cvt_f32_ubyte0_e32 v180, v180
	v_pk_mul_f32 v[188:189], v[188:189], v[192:193]
	v_rcp_iflag_f32_e32 v185, v180
	v_max_u32_sdwa v180, v181, v223 dst_sel:DWORD dst_unused:UNUSED_PAD src0_sel:BYTE_0 src1_sel:DWORD
	v_max_u32_sdwa v1, v1, v223 dst_sel:DWORD dst_unused:UNUSED_PAD src0_sel:BYTE_0 src1_sel:DWORD
	v_pk_mul_f32 v[122:123], v[122:123], v[188:189]
;     static __device__ __forceinline__ float gb(unsigned w, int sh) { return (float)max((w >> sh) & 0xffu, 1u); }
;     __device__ __forceinline__ void chain(f32x4 (&acc)[2][2][4][2], const pg8::Unit& u, bool has_next, int wr, int wc, int fr, int fq) const {
;     ...
;                 for (int m = 0; m < 4; ++m)
; #pragma unroll
;                     for (int bj = 0; bj < 2; ++bj) {
;                         const u32x2 a = ga[2 * m + bj], n = gn[2 * m + bj];
;                         f32x4 v0 = acc[h2][bj][m][0], v1 = acc[h2][bj][m][1];
;                         v0[0] *= gb(a.x, 0) * __builtin_amdgcn_rcpf(gb(n.x, 0)); v0[1] *= gb(a.x, 8) * __builtin_amdgcn_rcpf(gb(n.x, 8));
;                         v0[2] *= gb(a.x, 16) * __builtin_amdgcn_rcpf(gb(n.x, 16)); v0[3] *= gb(a.x, 24) * __builtin_amdgcn_rcpf(gb(n.x, 24));
;                         v1[0] *= gb(a.y, 0) * __builtin_amdgcn_rcpf(gb(n.y, 0)); v1[1] *= gb(a.y, 8) * __builtin_amdgcn_rcpf(gb(n.y, 8));
;                         v1[2] *= gb(a.y, 16) * __builtin_amdgcn_rcpf(gb(n.y, 16)); v1[3] *= gb(a.y, 24) * __builtin_amdgcn_rcpf(gb(n.y, 24));
;                         acc[h2][bj][m][0] = v0; acc[h2][bj][m][1] = v1;
	v_max_u32_sdwa v188, v181, v223 dst_sel:DWORD dst_unused:UNUSED_PAD src0_sel:BYTE_2 src1_sel:DWORD
	v_max_u32_sdwa v189, v181, v223 dst_sel:DWORD dst_unused:UNUSED_PAD src0_sel:BYTE_3 src1_sel:DWORD
	v_cvt_f32_ubyte0_e32 v181, v1
	v_cvt_f32_ubyte0_e32 v180, v180
	v_pk_mul_f32 v[180:181], v[186:187], v[180:181]
	v_cvt_f32_ubyte0_e32 v189, v189
	v_cvt_f32_ubyte0_e32 v188, v188
	v_pk_mul_f32 v[116:117], v[116:117], v[180:181]
	v_max_u32_sdwa v1, v174, v223 dst_sel:DWORD dst_unused:UNUSED_PAD src0_sel:BYTE_0 src1_sel:DWORD
	v_max_u32_sdwa v181, v174, v223 dst_sel:DWORD dst_unused:UNUSED_PAD src0_sel:BYTE_1 src1_sel:DWORD
	v_pk_mul_f32 v[184:185], v[184:185], v[188:189]
	v_cvt_f32_ubyte0_e32 v1, v1
	v_cvt_f32_ubyte0_e32 v181, v181
	v_pk_mul_f32 v[118:119], v[118:119], v[184:185]
	v_rcp_iflag_f32_e32 v180, v1
	v_rcp_iflag_f32_e32 v181, v181
	v_max_u32_sdwa v184, v174, v223 dst_sel:DWORD dst_unused:UNUSED_PAD src0_sel:BYTE_2 src1_sel:DWORD
	v_max_u32_sdwa v174, v174, v223 dst_sel:DWORD dst_unused:UNUSED_PAD src0_sel:BYTE_3 src1_sel:DWORD
	v_lshrrev_b32_e32 v1, 8, v168
	v_cvt_f32_ubyte0_e32 v174, v174
	v_rcp_iflag_f32_e32 v185, v174
	v_max_u32_sdwa v174, v168, v223 dst_sel:DWORD dst_unused:UNUSED_PAD src0_sel:BYTE_0 src1_sel:DWORD
	v_max_u32_sdwa v1, v1, v223 dst_sel:DWORD dst_unused:UNUSED_PAD src0_sel:BYTE_0 src1_sel:DWORD
	v_max_u32_sdwa v188, v168, v223 dst_sel:DWORD dst_unused:UNUSED_PAD src0_sel:BYTE_2 src1_sel:DWORD
	v_max_u32_sdwa v168, v168, v223 dst_sel:DWORD dst_unused:UNUSED_PAD src0_sel:BYTE_3 src1_sel:DWORD
	v_cvt_f32_ubyte0_e32 v187, v1
	v_cvt_f32_ubyte0_e32 v186, v174
	v_cvt_f32_ubyte0_e32 v189, v168
	v_max_u32_sdwa v168, v175, v223 dst_sel:DWORD dst_unused:UNUSED_PAD src0_sel:BYTE_1 src1_sel:DWORD
	v_cvt_f32_ubyte0_e32 v184, v184
	v_pk_mul_f32 v[180:181], v[180:181], v[186:187]
	v_cvt_f32_ubyte0_e32 v168, v168
	v_rcp_iflag_f32_e32 v184, v184
	v_pk_mul_f32 v[88:89], v[88:89], v[180:181]
	v_max_u32_sdwa v1, v175, v223 dst_sel:DWORD dst_unused:UNUSED_PAD src0_sel:BYTE_0 src1_sel:DWORD
	v_rcp_iflag_f32_e32 v181, v168
	v_max_u32_sdwa v168, v175, v223 dst_sel:DWORD dst_unused:UNUSED_PAD src0_sel:BYTE_2 src1_sel:DWORD
	v_cvt_f32_ubyte0_e32 v1, v1
	v_cvt_f32_ubyte0_e32 v168, v168
	v_rcp_iflag_f32_e32 v180, v1
	v_rcp_iflag_f32_e32 v174, v168
	v_max_u32_sdwa v168, v175, v223 dst_sel:DWORD dst_unused:UNUSED_PAD src0_sel:BYTE_3 src1_sel:DWORD
	v_cvt_f32_ubyte0_e32 v188, v188
	v_lshrrev_b32_e32 v1, 8, v169
	v_cvt_f32_ubyte0_e32 v168, v168
	v_pk_mul_f32 v[184:185], v[184:185], v[188:189]
	v_rcp_iflag_f32_e32 v175, v168
	v_max_u32_sdwa v168, v169, v223 dst_sel:DWORD dst_unused:UNUSED_PAD src0_sel:BYTE_0 src1_sel:DWORD
	v_max_u32_sdwa v1, v1, v223 dst_sel:DWORD dst_unused:UNUSED_PAD src0_sel:BYTE_0 src1_sel:DWORD
	v_pk_mul_f32 v[90:91], v[90:91], v[184:185]
	v_max_u32_sdwa v184, v169, v223 dst_sel:DWORD dst_unused:UNUSED_PAD src0_sel:BYTE_2 src1_sel:DWORD
	v_max_u32_sdwa v185, v169, v223 dst_sel:DWORD dst_unused:UNUSED_PAD src0_sel:BYTE_3 src1_sel:DWORD
	v_cvt_f32_ubyte0_e32 v169, v1
	v_cvt_f32_ubyte0_e32 v168, v168
	v_pk_mul_f32 v[168:169], v[180:181], v[168:169]
	v_cvt_f32_ubyte0_e32 v185, v185
	v_cvt_f32_ubyte0_e32 v184, v184
	v_pk_mul_f32 v[84:85], v[84:85], v[168:169]
	v_max_u32_sdwa v1, v182, v223 dst_sel:DWORD dst_unused:UNUSED_PAD src0_sel:BYTE_0 src1_sel:DWORD
	v_max_u32_sdwa v169, v182, v223 dst_sel:DWORD dst_unused:UNUSED_PAD src0_sel:BYTE_1 src1_sel:DWORD
	v_pk_mul_f32 v[174:175], v[174:175], v[184:185]
	v_cvt_f32_ubyte0_e32 v1, v1
	v_cvt_f32_ubyte0_e32 v169, v169
	v_pk_mul_f32 v[86:87], v[86:87], v[174:175]
	v_rcp_iflag_f32_e32 v168, v1
	v_rcp_iflag_f32_e32 v169, v169
	v_max_u32_sdwa v174, v182, v223 dst_sel:DWORD dst_unused:UNUSED_PAD src0_sel:BYTE_2 src1_sel:DWORD
	v_max_u32_sdwa v175, v182, v223 dst_sel:DWORD dst_unused:UNUSED_PAD src0_sel:BYTE_3 src1_sel:DWORD
	v_lshrrev_b32_e32 v1, 8, v170
	v_cvt_f32_ubyte0_e32 v174, v174
	v_cvt_f32_ubyte0_e32 v175, v175
	v_rcp_iflag_f32_e32 v174, v174
	v_rcp_iflag_f32_e32 v175, v175
	v_max_u32_sdwa v180, v170, v223 dst_sel:DWORD dst_unused:UNUSED_PAD src0_sel:BYTE_0 src1_sel:DWORD
	v_max_u32_sdwa v1, v1, v223 dst_sel:DWORD dst_unused:UNUSED_PAD src0_sel:BYTE_0 src1_sel:DWORD
	v_cvt_f32_ubyte0_e32 v181, v1
	v_cvt_f32_ubyte0_e32 v180, v180
	v_max_u32_sdwa v182, v170, v223 dst_sel:DWORD dst_unused:UNUSED_PAD src0_sel:BYTE_2 src1_sel:DWORD
	v_max_u32_sdwa v170, v170, v223 dst_sel:DWORD dst_unused:UNUSED_PAD src0_sel:BYTE_3 src1_sel:DWORD
	v_pk_mul_f32 v[168:169], v[168:169], v[180:181]
	v_cvt_f32_ubyte0_e32 v185, v170
	v_cvt_f32_ubyte0_e32 v184, v182
	v_pk_mul_f32 v[112:113], v[112:113], v[168:169]
	v_max_u32_sdwa v1, v183, v223 dst_sel:DWORD dst_unused:UNUSED_PAD src0_sel:BYTE_0 src1_sel:DWORD
	v_max_u32_sdwa v169, v183, v223 dst_sel:DWORD dst_unused:UNUSED_PAD src0_sel:BYTE_1 src1_sel:DWORD
	v_max_u32_sdwa v170, v183, v223 dst_sel:DWORD dst_unused:UNUSED_PAD src0_sel:BYTE_2 src1_sel:DWORD
	v_pk_mul_f32 v[174:175], v[174:175], v[184:185]
	v_cvt_f32_ubyte0_e32 v1, v1
	v_cvt_f32_ubyte0_e32 v169, v169
	v_cvt_f32_ubyte0_e32 v170, v170
	v_pk_mul_f32 v[114:115], v[114:115], v[174:175]
	v_rcp_iflag_f32_e32 v168, v1
	v_rcp_iflag_f32_e32 v169, v169
	v_rcp_iflag_f32_e32 v174, v170
	v_max_u32_sdwa v170, v183, v223 dst_sel:DWORD dst_unused:UNUSED_PAD src0_sel:BYTE_3 src1_sel:DWORD
	v_lshrrev_b32_e32 v1, 8, v171
	v_cvt_f32_ubyte0_e32 v170, v170
	v_rcp_iflag_f32_e32 v175, v170
	v_max_u32_sdwa v170, v171, v223 dst_sel:DWORD dst_unused:UNUSED_PAD src0_sel:BYTE_0 src1_sel:DWORD
	v_max_u32_sdwa v1, v1, v223 dst_sel:DWORD dst_unused:UNUSED_PAD src0_sel:BYTE_0 src1_sel:DWORD
;     static __device__ __forceinline__ float gb(unsigned w, int sh) { return (float)max((w >> sh) & 0xffu, 1u); }
;     __device__ __forceinline__ void chain(f32x4 (&acc)[2][2][4][2], const pg8::Unit& u, bool has_next, int wr, int wc, int fr, int fq) const {
;     ...
;                 for (int m = 0; m < 4; ++m)
; #pragma unroll
;                     for (int bj = 0; bj < 2; ++bj) {
;                         const u32x2 a = ga[2 * m + bj], n = gn[2 * m + bj];
;                         f32x4 v0 = acc[h2][bj][m][0], v1 = acc[h2][bj][m][1];
;                         v0[0] *= gb(a.x, 0) * __builtin_amdgcn_rcpf(gb(n.x, 0)); v0[1] *= gb(a.x, 8) * __builtin_amdgcn_rcpf(gb(n.x, 8));
;                         v0[2] *= gb(a.x, 16) * __builtin_amdgcn_rcpf(gb(n.x, 16)); v0[3] *= gb(a.x, 24) * __builtin_amdgcn_rcpf(gb(n.x, 24));
;                         v1[0] *= gb(a.y, 0) * __builtin_amdgcn_rcpf(gb(n.y, 0)); v1[1] *= gb(a.y, 8) * __builtin_amdgcn_rcpf(gb(n.y, 8));
;                         v1[2] *= gb(a.y, 16) * __builtin_amdgcn_rcpf(gb(n.y, 16)); v1[3] *= gb(a.y, 24) * __builtin_amdgcn_rcpf(gb(n.y, 24));
;                         acc[h2][bj][m][0] = v0; acc[h2][bj][m][1] = v1;
	v_max_u32_sdwa v180, v171, v223 dst_sel:DWORD dst_unused:UNUSED_PAD src0_sel:BYTE_2 src1_sel:DWORD
	v_max_u32_sdwa v181, v171, v223 dst_sel:DWORD dst_unused:UNUSED_PAD src0_sel:BYTE_3 src1_sel:DWORD
	v_cvt_f32_ubyte0_e32 v171, v1
	v_cvt_f32_ubyte0_e32 v170, v170
	v_pk_mul_f32 v[168:169], v[168:169], v[170:171]
	v_cvt_f32_ubyte0_e32 v181, v181
	v_cvt_f32_ubyte0_e32 v180, v180
	v_pk_mul_f32 v[108:109], v[108:109], v[168:169]
	v_max_u32_sdwa v1, v178, v223 dst_sel:DWORD dst_unused:UNUSED_PAD src0_sel:BYTE_0 src1_sel:DWORD
	v_max_u32_sdwa v169, v178, v223 dst_sel:DWORD dst_unused:UNUSED_PAD src0_sel:BYTE_1 src1_sel:DWORD
	v_pk_mul_f32 v[170:171], v[174:175], v[180:181]
	v_cvt_f32_ubyte0_e32 v1, v1
	v_cvt_f32_ubyte0_e32 v169, v169
	v_pk_mul_f32 v[110:111], v[110:111], v[170:171]
	v_rcp_iflag_f32_e32 v168, v1
	v_rcp_iflag_f32_e32 v169, v169
	v_max_u32_sdwa v170, v178, v223 dst_sel:DWORD dst_unused:UNUSED_PAD src0_sel:BYTE_2 src1_sel:DWORD
	v_max_u32_sdwa v171, v178, v223 dst_sel:DWORD dst_unused:UNUSED_PAD src0_sel:BYTE_3 src1_sel:DWORD
	v_lshrrev_b32_e32 v1, 8, v176
	v_cvt_f32_ubyte0_e32 v170, v170
	v_cvt_f32_ubyte0_e32 v171, v171
	v_rcp_iflag_f32_e32 v170, v170
	v_rcp_iflag_f32_e32 v171, v171
	v_max_u32_sdwa v174, v176, v223 dst_sel:DWORD dst_unused:UNUSED_PAD src0_sel:BYTE_0 src1_sel:DWORD
	v_max_u32_sdwa v1, v1, v223 dst_sel:DWORD dst_unused:UNUSED_PAD src0_sel:BYTE_0 src1_sel:DWORD
	v_cvt_f32_ubyte0_e32 v175, v1
	v_cvt_f32_ubyte0_e32 v174, v174
	v_max_u32_sdwa v178, v176, v223 dst_sel:DWORD dst_unused:UNUSED_PAD src0_sel:BYTE_2 src1_sel:DWORD
	v_max_u32_sdwa v176, v176, v223 dst_sel:DWORD dst_unused:UNUSED_PAD src0_sel:BYTE_3 src1_sel:DWORD
	v_pk_mul_f32 v[168:169], v[168:169], v[174:175]
	v_cvt_f32_ubyte0_e32 v181, v176
	v_cvt_f32_ubyte0_e32 v180, v178
	v_pk_mul_f32 v[80:81], v[80:81], v[168:169]
	v_max_u32_sdwa v1, v179, v223 dst_sel:DWORD dst_unused:UNUSED_PAD src0_sel:BYTE_0 src1_sel:DWORD
	v_max_u32_sdwa v169, v179, v223 dst_sel:DWORD dst_unused:UNUSED_PAD src0_sel:BYTE_1 src1_sel:DWORD
	v_pk_mul_f32 v[170:171], v[170:171], v[180:181]
	v_cvt_f32_ubyte0_e32 v1, v1
	v_cvt_f32_ubyte0_e32 v169, v169
	v_pk_mul_f32 v[82:83], v[82:83], v[170:171]
	v_rcp_iflag_f32_e32 v168, v1
	v_rcp_iflag_f32_e32 v169, v169
	v_max_u32_sdwa v170, v179, v223 dst_sel:DWORD dst_unused:UNUSED_PAD src0_sel:BYTE_2 src1_sel:DWORD
	v_max_u32_sdwa v171, v179, v223 dst_sel:DWORD dst_unused:UNUSED_PAD src0_sel:BYTE_3 src1_sel:DWORD
	v_lshrrev_b32_e32 v1, 8, v177
	v_cvt_f32_ubyte0_e32 v170, v170
	v_cvt_f32_ubyte0_e32 v171, v171
	v_rcp_iflag_f32_e32 v170, v170
	v_rcp_iflag_f32_e32 v171, v171
	v_max_u32_sdwa v174, v177, v223 dst_sel:DWORD dst_unused:UNUSED_PAD src0_sel:BYTE_0 src1_sel:DWORD
	v_max_u32_sdwa v1, v1, v223 dst_sel:DWORD dst_unused:UNUSED_PAD src0_sel:BYTE_0 src1_sel:DWORD
	v_cvt_f32_ubyte0_e32 v175, v1
	v_cvt_f32_ubyte0_e32 v174, v174
	v_max_u32_sdwa v176, v177, v223 dst_sel:DWORD dst_unused:UNUSED_PAD src0_sel:BYTE_2 src1_sel:DWORD
	v_max_u32_sdwa v177, v177, v223 dst_sel:DWORD dst_unused:UNUSED_PAD src0_sel:BYTE_3 src1_sel:DWORD
	v_pk_mul_f32 v[168:169], v[168:169], v[174:175]
	v_cvt_f32_ubyte0_e32 v177, v177
	v_cvt_f32_ubyte0_e32 v176, v176
	v_pk_mul_f32 v[76:77], v[76:77], v[168:169]
	v_max_u32_sdwa v1, v172, v223 dst_sel:DWORD dst_unused:UNUSED_PAD src0_sel:BYTE_0 src1_sel:DWORD
	v_max_u32_sdwa v169, v172, v223 dst_sel:DWORD dst_unused:UNUSED_PAD src0_sel:BYTE_1 src1_sel:DWORD
	v_pk_mul_f32 v[170:171], v[170:171], v[176:177]
	v_cvt_f32_ubyte0_e32 v1, v1
	v_cvt_f32_ubyte0_e32 v169, v169
	v_pk_mul_f32 v[78:79], v[78:79], v[170:171]
	v_rcp_iflag_f32_e32 v168, v1
	v_rcp_iflag_f32_e32 v169, v169
	v_max_u32_sdwa v170, v172, v223 dst_sel:DWORD dst_unused:UNUSED_PAD src0_sel:BYTE_2 src1_sel:DWORD
	v_max_u32_sdwa v171, v172, v223 dst_sel:DWORD dst_unused:UNUSED_PAD src0_sel:BYTE_3 src1_sel:DWORD
	v_lshrrev_b32_e32 v1, 8, v166
	v_cvt_f32_ubyte0_e32 v170, v170
	v_cvt_f32_ubyte0_e32 v171, v171
	v_rcp_iflag_f32_e32 v170, v170
	v_rcp_iflag_f32_e32 v171, v171
	v_max_u32_sdwa v172, v166, v223 dst_sel:DWORD dst_unused:UNUSED_PAD src0_sel:BYTE_0 src1_sel:DWORD
	v_max_u32_sdwa v1, v1, v223 dst_sel:DWORD dst_unused:UNUSED_PAD src0_sel:BYTE_0 src1_sel:DWORD
	v_max_u32_sdwa v176, v166, v223 dst_sel:DWORD dst_unused:UNUSED_PAD src0_sel:BYTE_2 src1_sel:DWORD
	v_max_u32_sdwa v166, v166, v223 dst_sel:DWORD dst_unused:UNUSED_PAD src0_sel:BYTE_3 src1_sel:DWORD
	v_cvt_f32_ubyte0_e32 v175, v1
	v_cvt_f32_ubyte0_e32 v174, v172
	v_cvt_f32_ubyte0_e32 v177, v166
	v_max_u32_sdwa v166, v173, v223 dst_sel:DWORD dst_unused:UNUSED_PAD src0_sel:BYTE_1 src1_sel:DWORD
	v_pk_mul_f32 v[168:169], v[168:169], v[174:175]
	v_cvt_f32_ubyte0_e32 v166, v166
	v_cvt_f32_ubyte0_e32 v176, v176
	v_pk_mul_f32 v[104:105], v[104:105], v[168:169]
	v_max_u32_sdwa v1, v173, v223 dst_sel:DWORD dst_unused:UNUSED_PAD src0_sel:BYTE_0 src1_sel:DWORD
	v_rcp_iflag_f32_e32 v169, v166
	v_max_u32_sdwa v166, v173, v223 dst_sel:DWORD dst_unused:UNUSED_PAD src0_sel:BYTE_2 src1_sel:DWORD
	v_pk_mul_f32 v[170:171], v[170:171], v[176:177]
	v_cvt_f32_ubyte0_e32 v1, v1
	v_cvt_f32_ubyte0_e32 v166, v166
	v_pk_mul_f32 v[106:107], v[106:107], v[170:171]
	v_rcp_iflag_f32_e32 v168, v1
	v_rcp_iflag_f32_e32 v170, v166
	v_max_u32_sdwa v166, v173, v223 dst_sel:DWORD dst_unused:UNUSED_PAD src0_sel:BYTE_3 src1_sel:DWORD
	v_lshrrev_b32_e32 v1, 8, v167
	v_cvt_f32_ubyte0_e32 v166, v166
	v_rcp_iflag_f32_e32 v171, v166
	v_max_u32_sdwa v166, v167, v223 dst_sel:DWORD dst_unused:UNUSED_PAD src0_sel:BYTE_0 src1_sel:DWORD
	v_max_u32_sdwa v1, v1, v223 dst_sel:DWORD dst_unused:UNUSED_PAD src0_sel:BYTE_0 src1_sel:DWORD
; #define GAS __attribute__((address_space(1)))
;     static __device__ __forceinline__ float gb(unsigned w, int sh) { return (float)max((w >> sh) & 0xffu, 1u); }
;     __device__ __forceinline__ void chain(f32x4 (&acc)[2][2][4][2], const pg8::Unit& u, bool has_next, int wr, int wc, int fr, int fq) const {
;     ...
;             for (int h2 = 0; h2 < 2; ++h2) {
;                 u32x2 ga[8], gn[8];
; #pragma unroll
;                 for (int m = 0; m < 4; ++m)
; #pragma unroll
;                     for (int bj = 0; bj < 2; ++bj) { const int o = (h2 * 128 + m * 16) * 256 + bj * 128; ga[2 * m + bj] = *(const GAS u32x2*)(ga_p + o); gn[2 * m + bj] = *(const GAS u32x2*)(ga_p + 65536 + o); }
; #pragma unroll
;                 for (int m = 0; m < 4; ++m)
; #pragma unroll
;                     for (int bj = 0; bj < 2; ++bj) {
;                         const u32x2 a = ga[2 * m + bj], n = gn[2 * m + bj];
;                         f32x4 v0 = acc[h2][bj][m][0], v1 = acc[h2][bj][m][1];
;                         v0[0] *= gb(a.x, 0) * __builtin_amdgcn_rcpf(gb(n.x, 0)); v0[1] *= gb(a.x, 8) * __builtin_amdgcn_rcpf(gb(n.x, 8));
;                         v0[2] *= gb(a.x, 16) * __builtin_amdgcn_rcpf(gb(n.x, 16)); v0[3] *= gb(a.x, 24) * __builtin_amdgcn_rcpf(gb(n.x, 24));
;                         v1[0] *= gb(a.y, 0) * __builtin_amdgcn_rcpf(gb(n.y, 0)); v1[1] *= gb(a.y, 8) * __builtin_amdgcn_rcpf(gb(n.y, 8));
;                         v1[2] *= gb(a.y, 16) * __builtin_amdgcn_rcpf(gb(n.y, 16)); v1[3] *= gb(a.y, 24) * __builtin_amdgcn_rcpf(gb(n.y, 24));
;                         acc[h2][bj][m][0] = v0; acc[h2][bj][m][1] = v1;
	v_max_u32_sdwa v172, v167, v223 dst_sel:DWORD dst_unused:UNUSED_PAD src0_sel:BYTE_2 src1_sel:DWORD
	v_max_u32_sdwa v173, v167, v223 dst_sel:DWORD dst_unused:UNUSED_PAD src0_sel:BYTE_3 src1_sel:DWORD
	v_cvt_f32_ubyte0_e32 v167, v1
	v_cvt_f32_ubyte0_e32 v166, v166
	v_pk_mul_f32 v[166:167], v[168:169], v[166:167]
	v_cvt_f32_ubyte0_e32 v173, v173
	v_cvt_f32_ubyte0_e32 v172, v172
	v_pk_mul_f32 v[100:101], v[100:101], v[166:167]
	v_max_u32_sdwa v1, v164, v223 dst_sel:DWORD dst_unused:UNUSED_PAD src0_sel:BYTE_0 src1_sel:DWORD
	v_max_u32_sdwa v167, v164, v223 dst_sel:DWORD dst_unused:UNUSED_PAD src0_sel:BYTE_1 src1_sel:DWORD
	v_pk_mul_f32 v[168:169], v[170:171], v[172:173]
	v_cvt_f32_ubyte0_e32 v1, v1
	v_cvt_f32_ubyte0_e32 v167, v167
	v_pk_mul_f32 v[102:103], v[102:103], v[168:169]
	v_rcp_iflag_f32_e32 v166, v1
	v_rcp_iflag_f32_e32 v167, v167
	v_max_u32_sdwa v168, v164, v223 dst_sel:DWORD dst_unused:UNUSED_PAD src0_sel:BYTE_2 src1_sel:DWORD
	v_max_u32_sdwa v164, v164, v223 dst_sel:DWORD dst_unused:UNUSED_PAD src0_sel:BYTE_3 src1_sel:DWORD
	v_lshrrev_b32_e32 v1, 8, v162
	v_cvt_f32_ubyte0_e32 v164, v164
	v_rcp_iflag_f32_e32 v169, v164
	v_max_u32_sdwa v164, v162, v223 dst_sel:DWORD dst_unused:UNUSED_PAD src0_sel:BYTE_0 src1_sel:DWORD
	v_max_u32_sdwa v1, v1, v223 dst_sel:DWORD dst_unused:UNUSED_PAD src0_sel:BYTE_0 src1_sel:DWORD
	v_max_u32_sdwa v172, v162, v223 dst_sel:DWORD dst_unused:UNUSED_PAD src0_sel:BYTE_2 src1_sel:DWORD
	v_max_u32_sdwa v162, v162, v223 dst_sel:DWORD dst_unused:UNUSED_PAD src0_sel:BYTE_3 src1_sel:DWORD
	v_cvt_f32_ubyte0_e32 v171, v1
	v_cvt_f32_ubyte0_e32 v170, v164
	v_cvt_f32_ubyte0_e32 v173, v162
	v_max_u32_sdwa v162, v165, v223 dst_sel:DWORD dst_unused:UNUSED_PAD src0_sel:BYTE_1 src1_sel:DWORD
	v_cvt_f32_ubyte0_e32 v168, v168
	v_pk_mul_f32 v[166:167], v[166:167], v[170:171]
	v_cvt_f32_ubyte0_e32 v162, v162
	v_rcp_iflag_f32_e32 v168, v168
	v_pk_mul_f32 v[72:73], v[72:73], v[166:167]
	v_max_u32_sdwa v1, v165, v223 dst_sel:DWORD dst_unused:UNUSED_PAD src0_sel:BYTE_0 src1_sel:DWORD
	v_rcp_iflag_f32_e32 v167, v162
	v_max_u32_sdwa v162, v165, v223 dst_sel:DWORD dst_unused:UNUSED_PAD src0_sel:BYTE_2 src1_sel:DWORD
	v_cvt_f32_ubyte0_e32 v1, v1
	v_cvt_f32_ubyte0_e32 v162, v162
	v_rcp_iflag_f32_e32 v166, v1
	v_rcp_iflag_f32_e32 v164, v162
	v_max_u32_sdwa v162, v165, v223 dst_sel:DWORD dst_unused:UNUSED_PAD src0_sel:BYTE_3 src1_sel:DWORD
	v_cvt_f32_ubyte0_e32 v172, v172
	v_lshrrev_b32_e32 v1, 8, v163
	v_cvt_f32_ubyte0_e32 v162, v162
	v_pk_mul_f32 v[168:169], v[168:169], v[172:173]
	v_rcp_iflag_f32_e32 v165, v162
	v_max_u32_sdwa v162, v163, v223 dst_sel:DWORD dst_unused:UNUSED_PAD src0_sel:BYTE_0 src1_sel:DWORD
	v_max_u32_sdwa v1, v1, v223 dst_sel:DWORD dst_unused:UNUSED_PAD src0_sel:BYTE_0 src1_sel:DWORD
	v_pk_mul_f32 v[74:75], v[74:75], v[168:169]
	v_max_u32_sdwa v168, v163, v223 dst_sel:DWORD dst_unused:UNUSED_PAD src0_sel:BYTE_2 src1_sel:DWORD
	v_max_u32_sdwa v169, v163, v223 dst_sel:DWORD dst_unused:UNUSED_PAD src0_sel:BYTE_3 src1_sel:DWORD
	v_cvt_f32_ubyte0_e32 v163, v1
	v_cvt_f32_ubyte0_e32 v162, v162
	v_pk_mul_f32 v[162:163], v[166:167], v[162:163]
	v_cvt_f32_ubyte0_e32 v169, v169
	v_cvt_f32_ubyte0_e32 v168, v168
	v_pk_mul_f32 v[68:69], v[68:69], v[162:163]
	v_add_co_u32_e32 v162, vcc, s68, v2
	v_pk_mul_f32 v[164:165], v[164:165], v[168:169]
	s_nop 0
	v_addc_co_u32_e32 v163, vcc, 0, v3, vcc
	v_pk_mul_f32 v[70:71], v[70:71], v[164:165]
	v_add_co_u32_e32 v164, vcc, s69, v2
	s_nop 1
	v_addc_co_u32_e32 v165, vcc, 0, v3, vcc
	v_add_co_u32_e32 v166, vcc, s57, v2
	global_load_dwordx2 v[174:175], v[164:165], off offset:-4096 sc1
	s_nop 0
	v_addc_co_u32_e32 v167, vcc, 0, v3, vcc
	v_add_co_u32_e32 v178, vcc, s16, v2
	s_mov_b32 s16, 0x1a000
	s_nop 0
	v_addc_co_u32_e32 v179, vcc, 0, v3, vcc
	global_load_dwordx2 v[176:177], v[178:179], off offset:-4096 sc1
	global_load_dwordx2 v[170:171], v[162:163], off offset:128 sc1
	global_load_dwordx2 v[172:173], v[166:167], off offset:128 sc1
	s_nop 0
	global_load_dwordx2 v[166:167], v[164:165], off sc1
	global_load_dwordx2 v[168:169], v[178:179], off sc1
	global_load_dwordx2 v[162:163], v[164:165], off offset:128 sc1
	s_nop 0
	global_load_dwordx2 v[164:165], v[178:179], off offset:128 sc1
	v_add_co_u32_e32 v178, vcc, s62, v2
	s_waitcnt vmcnt(0)
; #define GAS __attribute__((address_space(1)))
;     static __device__ __forceinline__ float gb(unsigned w, int sh) { return (float)max((w >> sh) & 0xffu, 1u); }
;     __device__ __forceinline__ void chain(f32x4 (&acc)[2][2][4][2], const pg8::Unit& u, bool has_next, int wr, int wc, int fr, int fq) const {
;     ...
;             for (int h2 = 0; h2 < 2; ++h2) {
;                 u32x2 ga[8], gn[8];
; #pragma unroll
;                 for (int m = 0; m < 4; ++m)
; #pragma unroll
;                     for (int bj = 0; bj < 2; ++bj) { const int o = (h2 * 128 + m * 16) * 256 + bj * 128; ga[2 * m + bj] = *(const GAS u32x2*)(ga_p + o); gn[2 * m + bj] = *(const GAS u32x2*)(ga_p + 65536 + o); }
; #pragma unroll
;                 for (int m = 0; m < 4; ++m)
; #pragma unroll
;                     for (int bj = 0; bj < 2; ++bj) {
;                         const u32x2 a = ga[2 * m + bj], n = gn[2 * m + bj];
;                         f32x4 v0 = acc[h2][bj][m][0], v1 = acc[h2][bj][m][1];
;                         v0[0] *= gb(a.x, 0) * __builtin_amdgcn_rcpf(gb(n.x, 0)); v0[1] *= gb(a.x, 8) * __builtin_amdgcn_rcpf(gb(n.x, 8));
;                         v0[2] *= gb(a.x, 16) * __builtin_amdgcn_rcpf(gb(n.x, 16)); v0[3] *= gb(a.x, 24) * __builtin_amdgcn_rcpf(gb(n.x, 24));
;                         v1[0] *= gb(a.y, 0) * __builtin_amdgcn_rcpf(gb(n.y, 0)); v1[1] *= gb(a.y, 8) * __builtin_amdgcn_rcpf(gb(n.y, 8));
;                         v1[2] *= gb(a.y, 16) * __builtin_amdgcn_rcpf(gb(n.y, 16)); v1[3] *= gb(a.y, 24) * __builtin_amdgcn_rcpf(gb(n.y, 24));
;                         acc[h2][bj][m][0] = v0; acc[h2][bj][m][1] = v1;
	v_max_u32_sdwa v1, v176, v223 dst_sel:DWORD dst_unused:UNUSED_PAD src0_sel:BYTE_0 src1_sel:DWORD
	v_addc_co_u32_e32 v179, vcc, 0, v3, vcc
	v_add_co_u32_e32 v184, vcc, s63, v2
	v_max_u32_sdwa v193, v176, v223 dst_sel:DWORD dst_unused:UNUSED_PAD src0_sel:BYTE_1 src1_sel:DWORD
	s_nop 0
	v_addc_co_u32_e32 v185, vcc, 0, v3, vcc
	v_add_co_u32_e32 v188, vcc, s16, v2
	global_load_dwordx2 v[180:181], v[184:185], off offset:-4096 sc1
	s_nop 0
	v_addc_co_u32_e32 v189, vcc, 0, v3, vcc
	s_mov_b32 s16, 0x1b000
	v_add_co_u32_e32 v186, vcc, s16, v2
	v_cvt_f32_ubyte0_e32 v1, v1
	s_nop 0
	v_addc_co_u32_e32 v187, vcc, 0, v3, vcc
	global_load_dwordx2 v[182:183], v[186:187], off offset:-4096 sc1
	global_load_dwordx2 v[2:3], v[178:179], off offset:128 sc1
	s_nop 0
	global_load_dwordx2 v[178:179], v[188:189], off offset:128 sc1
	s_nop 0
	global_load_dwordx2 v[188:189], v[184:185], off sc1
	global_load_dwordx2 v[190:191], v[186:187], off sc1
	s_nop 0
	global_load_dwordx2 v[184:185], v[184:185], off offset:128 sc1
	s_nop 0
	global_load_dwordx2 v[186:187], v[186:187], off offset:128 sc1
	v_cvt_f32_ubyte0_e32 v193, v193
	v_rcp_iflag_f32_e32 v192, v1
	v_rcp_iflag_f32_e32 v193, v193
	v_max_u32_sdwa v197, v176, v223 dst_sel:DWORD dst_unused:UNUSED_PAD src0_sel:BYTE_2 src1_sel:DWORD
	v_max_u32_sdwa v176, v176, v223 dst_sel:DWORD dst_unused:UNUSED_PAD src0_sel:BYTE_3 src1_sel:DWORD
	v_lshrrev_b32_e32 v1, 8, v174
	v_cvt_f32_ubyte0_e32 v197, v197
	v_cvt_f32_ubyte0_e32 v176, v176
	v_rcp_iflag_f32_e32 v198, v197
	v_rcp_iflag_f32_e32 v199, v176
	v_max_u32_sdwa v176, v174, v223 dst_sel:DWORD dst_unused:UNUSED_PAD src0_sel:BYTE_0 src1_sel:DWORD
	v_max_u32_sdwa v1, v1, v223 dst_sel:DWORD dst_unused:UNUSED_PAD src0_sel:BYTE_0 src1_sel:DWORD
	v_max_u32_sdwa v197, v174, v223 dst_sel:DWORD dst_unused:UNUSED_PAD src0_sel:BYTE_2 src1_sel:DWORD
	v_max_u32_sdwa v174, v174, v223 dst_sel:DWORD dst_unused:UNUSED_PAD src0_sel:BYTE_3 src1_sel:DWORD
	v_cvt_f32_ubyte0_e32 v201, v1
	v_cvt_f32_ubyte0_e32 v200, v176
	v_cvt_f32_ubyte0_e32 v203, v174
	v_max_u32_sdwa v174, v177, v223 dst_sel:DWORD dst_unused:UNUSED_PAD src0_sel:BYTE_1 src1_sel:DWORD
	v_pk_mul_f32 v[192:193], v[192:193], v[200:201]
	v_cvt_f32_ubyte0_e32 v174, v174
	v_pk_mul_f32 v[64:65], v[64:65], v[192:193]
	v_max_u32_sdwa v1, v177, v223 dst_sel:DWORD dst_unused:UNUSED_PAD src0_sel:BYTE_0 src1_sel:DWORD
	v_rcp_iflag_f32_e32 v193, v174
	v_max_u32_sdwa v174, v177, v223 dst_sel:DWORD dst_unused:UNUSED_PAD src0_sel:BYTE_2 src1_sel:DWORD
	v_cvt_f32_ubyte0_e32 v1, v1
	v_cvt_f32_ubyte0_e32 v174, v174
	v_rcp_iflag_f32_e32 v192, v1
	v_rcp_iflag_f32_e32 v176, v174
	v_max_u32_sdwa v174, v177, v223 dst_sel:DWORD dst_unused:UNUSED_PAD src0_sel:BYTE_3 src1_sel:DWORD
	v_cvt_f32_ubyte0_e32 v202, v197
	v_lshrrev_b32_e32 v1, 8, v175
	v_cvt_f32_ubyte0_e32 v174, v174
	v_pk_mul_f32 v[198:199], v[198:199], v[202:203]
	v_rcp_iflag_f32_e32 v177, v174
	v_max_u32_sdwa v174, v175, v223 dst_sel:DWORD dst_unused:UNUSED_PAD src0_sel:BYTE_0 src1_sel:DWORD
	v_max_u32_sdwa v1, v1, v223 dst_sel:DWORD dst_unused:UNUSED_PAD src0_sel:BYTE_0 src1_sel:DWORD
	v_pk_mul_f32 v[66:67], v[66:67], v[198:199]
	v_max_u32_sdwa v197, v175, v223 dst_sel:DWORD dst_unused:UNUSED_PAD src0_sel:BYTE_2 src1_sel:DWORD
	v_max_u32_sdwa v198, v175, v223 dst_sel:DWORD dst_unused:UNUSED_PAD src0_sel:BYTE_3 src1_sel:DWORD
	v_cvt_f32_ubyte0_e32 v175, v1
	v_cvt_f32_ubyte0_e32 v174, v174
	v_pk_mul_f32 v[174:175], v[192:193], v[174:175]
	v_cvt_f32_ubyte0_e32 v199, v198
	v_cvt_f32_ubyte0_e32 v198, v197
	v_pk_mul_f32 v[60:61], v[60:61], v[174:175]
	v_max_u32_sdwa v1, v172, v223 dst_sel:DWORD dst_unused:UNUSED_PAD src0_sel:BYTE_0 src1_sel:DWORD
	v_max_u32_sdwa v175, v172, v223 dst_sel:DWORD dst_unused:UNUSED_PAD src0_sel:BYTE_1 src1_sel:DWORD
	v_pk_mul_f32 v[176:177], v[176:177], v[198:199]
	v_cvt_f32_ubyte0_e32 v1, v1
	v_cvt_f32_ubyte0_e32 v175, v175
	v_pk_mul_f32 v[62:63], v[62:63], v[176:177]
	v_rcp_iflag_f32_e32 v174, v1
	v_rcp_iflag_f32_e32 v175, v175
	v_max_u32_sdwa v176, v172, v223 dst_sel:DWORD dst_unused:UNUSED_PAD src0_sel:BYTE_2 src1_sel:DWORD
	v_max_u32_sdwa v172, v172, v223 dst_sel:DWORD dst_unused:UNUSED_PAD src0_sel:BYTE_3 src1_sel:DWORD
	v_lshrrev_b32_e32 v1, 8, v170
	v_cvt_f32_ubyte0_e32 v172, v172
	v_rcp_iflag_f32_e32 v177, v172
	v_max_u32_sdwa v172, v170, v223 dst_sel:DWORD dst_unused:UNUSED_PAD src0_sel:BYTE_0 src1_sel:DWORD
	v_max_u32_sdwa v1, v1, v223 dst_sel:DWORD dst_unused:UNUSED_PAD src0_sel:BYTE_0 src1_sel:DWORD
	v_max_u32_sdwa v197, v170, v223 dst_sel:DWORD dst_unused:UNUSED_PAD src0_sel:BYTE_2 src1_sel:DWORD
	v_max_u32_sdwa v170, v170, v223 dst_sel:DWORD dst_unused:UNUSED_PAD src0_sel:BYTE_3 src1_sel:DWORD
	v_cvt_f32_ubyte0_e32 v193, v1
	v_cvt_f32_ubyte0_e32 v192, v172
	v_cvt_f32_ubyte0_e32 v199, v170
	v_max_u32_sdwa v170, v173, v223 dst_sel:DWORD dst_unused:UNUSED_PAD src0_sel:BYTE_1 src1_sel:DWORD
	v_cvt_f32_ubyte0_e32 v176, v176
	v_pk_mul_f32 v[174:175], v[174:175], v[192:193]
	v_cvt_f32_ubyte0_e32 v170, v170
	v_rcp_iflag_f32_e32 v176, v176
	v_pk_mul_f32 v[32:33], v[32:33], v[174:175]
	v_max_u32_sdwa v1, v173, v223 dst_sel:DWORD dst_unused:UNUSED_PAD src0_sel:BYTE_0 src1_sel:DWORD
	v_rcp_iflag_f32_e32 v175, v170
	v_max_u32_sdwa v170, v173, v223 dst_sel:DWORD dst_unused:UNUSED_PAD src0_sel:BYTE_2 src1_sel:DWORD
	v_cvt_f32_ubyte0_e32 v1, v1
	v_cvt_f32_ubyte0_e32 v170, v170
	v_rcp_iflag_f32_e32 v174, v1
	v_rcp_iflag_f32_e32 v172, v170
	v_max_u32_sdwa v170, v173, v223 dst_sel:DWORD dst_unused:UNUSED_PAD src0_sel:BYTE_3 src1_sel:DWORD
	v_cvt_f32_ubyte0_e32 v198, v197
	v_lshrrev_b32_e32 v1, 8, v171
	v_cvt_f32_ubyte0_e32 v170, v170
	v_pk_mul_f32 v[176:177], v[176:177], v[198:199]
;     static __device__ __forceinline__ float gb(unsigned w, int sh) { return (float)max((w >> sh) & 0xffu, 1u); }
;     __device__ __forceinline__ void chain(f32x4 (&acc)[2][2][4][2], const pg8::Unit& u, bool has_next, int wr, int wc, int fr, int fq) const {
;     ...
;                 for (int m = 0; m < 4; ++m)
; #pragma unroll
;                     for (int bj = 0; bj < 2; ++bj) {
;                         const u32x2 a = ga[2 * m + bj], n = gn[2 * m + bj];
;                         f32x4 v0 = acc[h2][bj][m][0], v1 = acc[h2][bj][m][1];
;                         v0[0] *= gb(a.x, 0) * __builtin_amdgcn_rcpf(gb(n.x, 0)); v0[1] *= gb(a.x, 8) * __builtin_amdgcn_rcpf(gb(n.x, 8));
;                         v0[2] *= gb(a.x, 16) * __builtin_amdgcn_rcpf(gb(n.x, 16)); v0[3] *= gb(a.x, 24) * __builtin_amdgcn_rcpf(gb(n.x, 24));
;                         v1[0] *= gb(a.y, 0) * __builtin_amdgcn_rcpf(gb(n.y, 0)); v1[1] *= gb(a.y, 8) * __builtin_amdgcn_rcpf(gb(n.y, 8));
;                         v1[2] *= gb(a.y, 16) * __builtin_amdgcn_rcpf(gb(n.y, 16)); v1[3] *= gb(a.y, 24) * __builtin_amdgcn_rcpf(gb(n.y, 24));
;                         acc[h2][bj][m][0] = v0; acc[h2][bj][m][1] = v1;
	v_rcp_iflag_f32_e32 v173, v170
	v_max_u32_sdwa v170, v171, v223 dst_sel:DWORD dst_unused:UNUSED_PAD src0_sel:BYTE_0 src1_sel:DWORD
	v_max_u32_sdwa v1, v1, v223 dst_sel:DWORD dst_unused:UNUSED_PAD src0_sel:BYTE_0 src1_sel:DWORD
	v_pk_mul_f32 v[34:35], v[34:35], v[176:177]
	v_max_u32_sdwa v176, v171, v223 dst_sel:DWORD dst_unused:UNUSED_PAD src0_sel:BYTE_2 src1_sel:DWORD
	v_max_u32_sdwa v177, v171, v223 dst_sel:DWORD dst_unused:UNUSED_PAD src0_sel:BYTE_3 src1_sel:DWORD
	v_cvt_f32_ubyte0_e32 v171, v1
	v_cvt_f32_ubyte0_e32 v170, v170
	v_pk_mul_f32 v[170:171], v[174:175], v[170:171]
	v_cvt_f32_ubyte0_e32 v177, v177
	v_cvt_f32_ubyte0_e32 v176, v176
	v_pk_mul_f32 v[28:29], v[28:29], v[170:171]
	v_max_u32_sdwa v1, v168, v223 dst_sel:DWORD dst_unused:UNUSED_PAD src0_sel:BYTE_0 src1_sel:DWORD
	v_max_u32_sdwa v171, v168, v223 dst_sel:DWORD dst_unused:UNUSED_PAD src0_sel:BYTE_1 src1_sel:DWORD
	v_pk_mul_f32 v[172:173], v[172:173], v[176:177]
	v_cvt_f32_ubyte0_e32 v1, v1
	v_cvt_f32_ubyte0_e32 v171, v171
	v_pk_mul_f32 v[30:31], v[30:31], v[172:173]
	v_rcp_iflag_f32_e32 v170, v1
	v_rcp_iflag_f32_e32 v171, v171
	v_max_u32_sdwa v172, v168, v223 dst_sel:DWORD dst_unused:UNUSED_PAD src0_sel:BYTE_2 src1_sel:DWORD
	v_max_u32_sdwa v168, v168, v223 dst_sel:DWORD dst_unused:UNUSED_PAD src0_sel:BYTE_3 src1_sel:DWORD
	v_lshrrev_b32_e32 v1, 8, v166
	v_cvt_f32_ubyte0_e32 v168, v168
	v_rcp_iflag_f32_e32 v173, v168
	v_max_u32_sdwa v168, v166, v223 dst_sel:DWORD dst_unused:UNUSED_PAD src0_sel:BYTE_0 src1_sel:DWORD
	v_max_u32_sdwa v1, v1, v223 dst_sel:DWORD dst_unused:UNUSED_PAD src0_sel:BYTE_0 src1_sel:DWORD
	v_max_u32_sdwa v176, v166, v223 dst_sel:DWORD dst_unused:UNUSED_PAD src0_sel:BYTE_2 src1_sel:DWORD
	v_max_u32_sdwa v166, v166, v223 dst_sel:DWORD dst_unused:UNUSED_PAD src0_sel:BYTE_3 src1_sel:DWORD
	v_cvt_f32_ubyte0_e32 v175, v1
	v_cvt_f32_ubyte0_e32 v174, v168
	v_cvt_f32_ubyte0_e32 v177, v166
	v_max_u32_sdwa v166, v169, v223 dst_sel:DWORD dst_unused:UNUSED_PAD src0_sel:BYTE_1 src1_sel:DWORD
	v_cvt_f32_ubyte0_e32 v172, v172
	v_pk_mul_f32 v[170:171], v[170:171], v[174:175]
	v_cvt_f32_ubyte0_e32 v166, v166
	v_rcp_iflag_f32_e32 v172, v172
	v_pk_mul_f32 v[56:57], v[56:57], v[170:171]
	v_max_u32_sdwa v1, v169, v223 dst_sel:DWORD dst_unused:UNUSED_PAD src0_sel:BYTE_0 src1_sel:DWORD
	v_rcp_iflag_f32_e32 v171, v166
	v_max_u32_sdwa v166, v169, v223 dst_sel:DWORD dst_unused:UNUSED_PAD src0_sel:BYTE_2 src1_sel:DWORD
	v_cvt_f32_ubyte0_e32 v1, v1
	v_cvt_f32_ubyte0_e32 v166, v166
	v_rcp_iflag_f32_e32 v170, v1
	v_rcp_iflag_f32_e32 v168, v166
	v_max_u32_sdwa v166, v169, v223 dst_sel:DWORD dst_unused:UNUSED_PAD src0_sel:BYTE_3 src1_sel:DWORD
	v_cvt_f32_ubyte0_e32 v176, v176
	v_lshrrev_b32_e32 v1, 8, v167
	v_cvt_f32_ubyte0_e32 v166, v166
	v_pk_mul_f32 v[172:173], v[172:173], v[176:177]
	v_rcp_iflag_f32_e32 v169, v166
	v_max_u32_sdwa v166, v167, v223 dst_sel:DWORD dst_unused:UNUSED_PAD src0_sel:BYTE_0 src1_sel:DWORD
	v_max_u32_sdwa v1, v1, v223 dst_sel:DWORD dst_unused:UNUSED_PAD src0_sel:BYTE_0 src1_sel:DWORD
	v_pk_mul_f32 v[58:59], v[58:59], v[172:173]
	v_max_u32_sdwa v172, v167, v223 dst_sel:DWORD dst_unused:UNUSED_PAD src0_sel:BYTE_2 src1_sel:DWORD
	v_max_u32_sdwa v173, v167, v223 dst_sel:DWORD dst_unused:UNUSED_PAD src0_sel:BYTE_3 src1_sel:DWORD
	v_cvt_f32_ubyte0_e32 v167, v1
	v_cvt_f32_ubyte0_e32 v166, v166
	v_pk_mul_f32 v[166:167], v[170:171], v[166:167]
	v_cvt_f32_ubyte0_e32 v173, v173
	v_cvt_f32_ubyte0_e32 v172, v172
	v_pk_mul_f32 v[52:53], v[52:53], v[166:167]
	v_max_u32_sdwa v1, v164, v223 dst_sel:DWORD dst_unused:UNUSED_PAD src0_sel:BYTE_0 src1_sel:DWORD
	v_max_u32_sdwa v167, v164, v223 dst_sel:DWORD dst_unused:UNUSED_PAD src0_sel:BYTE_1 src1_sel:DWORD
	v_pk_mul_f32 v[168:169], v[168:169], v[172:173]
	v_cvt_f32_ubyte0_e32 v1, v1
	v_cvt_f32_ubyte0_e32 v167, v167
	v_pk_mul_f32 v[54:55], v[54:55], v[168:169]
	v_rcp_iflag_f32_e32 v166, v1
	v_rcp_iflag_f32_e32 v167, v167
	v_max_u32_sdwa v168, v164, v223 dst_sel:DWORD dst_unused:UNUSED_PAD src0_sel:BYTE_2 src1_sel:DWORD
	v_max_u32_sdwa v164, v164, v223 dst_sel:DWORD dst_unused:UNUSED_PAD src0_sel:BYTE_3 src1_sel:DWORD
	v_lshrrev_b32_e32 v1, 8, v162
	v_cvt_f32_ubyte0_e32 v164, v164
	v_rcp_iflag_f32_e32 v169, v164
	v_max_u32_sdwa v164, v162, v223 dst_sel:DWORD dst_unused:UNUSED_PAD src0_sel:BYTE_0 src1_sel:DWORD
	v_max_u32_sdwa v1, v1, v223 dst_sel:DWORD dst_unused:UNUSED_PAD src0_sel:BYTE_0 src1_sel:DWORD
	v_max_u32_sdwa v172, v162, v223 dst_sel:DWORD dst_unused:UNUSED_PAD src0_sel:BYTE_2 src1_sel:DWORD
	v_max_u32_sdwa v162, v162, v223 dst_sel:DWORD dst_unused:UNUSED_PAD src0_sel:BYTE_3 src1_sel:DWORD
	v_cvt_f32_ubyte0_e32 v171, v1
	v_cvt_f32_ubyte0_e32 v170, v164
	v_cvt_f32_ubyte0_e32 v173, v162
	v_max_u32_sdwa v162, v165, v223 dst_sel:DWORD dst_unused:UNUSED_PAD src0_sel:BYTE_1 src1_sel:DWORD
	v_cvt_f32_ubyte0_e32 v168, v168
	v_pk_mul_f32 v[166:167], v[166:167], v[170:171]
	v_cvt_f32_ubyte0_e32 v162, v162
	v_rcp_iflag_f32_e32 v168, v168
	v_pk_mul_f32 v[24:25], v[24:25], v[166:167]
	v_max_u32_sdwa v1, v165, v223 dst_sel:DWORD dst_unused:UNUSED_PAD src0_sel:BYTE_0 src1_sel:DWORD
	v_rcp_iflag_f32_e32 v167, v162
	v_max_u32_sdwa v162, v165, v223 dst_sel:DWORD dst_unused:UNUSED_PAD src0_sel:BYTE_2 src1_sel:DWORD
	v_cvt_f32_ubyte0_e32 v1, v1
	v_cvt_f32_ubyte0_e32 v162, v162
	v_rcp_iflag_f32_e32 v166, v1
	v_rcp_iflag_f32_e32 v164, v162
	v_max_u32_sdwa v162, v165, v223 dst_sel:DWORD dst_unused:UNUSED_PAD src0_sel:BYTE_3 src1_sel:DWORD
	v_cvt_f32_ubyte0_e32 v172, v172
	v_lshrrev_b32_e32 v1, 8, v163
	v_cvt_f32_ubyte0_e32 v162, v162
	v_pk_mul_f32 v[168:169], v[168:169], v[172:173]
	v_rcp_iflag_f32_e32 v165, v162
	v_max_u32_sdwa v162, v163, v223 dst_sel:DWORD dst_unused:UNUSED_PAD src0_sel:BYTE_0 src1_sel:DWORD
	v_max_u32_sdwa v1, v1, v223 dst_sel:DWORD dst_unused:UNUSED_PAD src0_sel:BYTE_0 src1_sel:DWORD
	v_pk_mul_f32 v[26:27], v[26:27], v[168:169]
	v_max_u32_sdwa v168, v163, v223 dst_sel:DWORD dst_unused:UNUSED_PAD src0_sel:BYTE_2 src1_sel:DWORD
	v_max_u32_sdwa v169, v163, v223 dst_sel:DWORD dst_unused:UNUSED_PAD src0_sel:BYTE_3 src1_sel:DWORD
	v_cvt_f32_ubyte0_e32 v163, v1
	v_cvt_f32_ubyte0_e32 v162, v162
	v_pk_mul_f32 v[162:163], v[166:167], v[162:163]
	v_cvt_f32_ubyte0_e32 v169, v169
	v_cvt_f32_ubyte0_e32 v168, v168
	v_pk_mul_f32 v[20:21], v[20:21], v[162:163]
	s_waitcnt vmcnt(0)
;     static __device__ __forceinline__ float gb(unsigned w, int sh) { return (float)max((w >> sh) & 0xffu, 1u); }
;     __device__ __forceinline__ void chain(f32x4 (&acc)[2][2][4][2], const pg8::Unit& u, bool has_next, int wr, int wc, int fr, int fq) const {
;     ...
;                 for (int m = 0; m < 4; ++m)
; #pragma unroll
;                     for (int bj = 0; bj < 2; ++bj) {
;                         const u32x2 a = ga[2 * m + bj], n = gn[2 * m + bj];
;                         f32x4 v0 = acc[h2][bj][m][0], v1 = acc[h2][bj][m][1];
;                         v0[0] *= gb(a.x, 0) * __builtin_amdgcn_rcpf(gb(n.x, 0)); v0[1] *= gb(a.x, 8) * __builtin_amdgcn_rcpf(gb(n.x, 8));
;                         v0[2] *= gb(a.x, 16) * __builtin_amdgcn_rcpf(gb(n.x, 16)); v0[3] *= gb(a.x, 24) * __builtin_amdgcn_rcpf(gb(n.x, 24));
;                         v1[0] *= gb(a.y, 0) * __builtin_amdgcn_rcpf(gb(n.y, 0)); v1[1] *= gb(a.y, 8) * __builtin_amdgcn_rcpf(gb(n.y, 8));
;                         v1[2] *= gb(a.y, 16) * __builtin_amdgcn_rcpf(gb(n.y, 16)); v1[3] *= gb(a.y, 24) * __builtin_amdgcn_rcpf(gb(n.y, 24));
;                         acc[h2][bj][m][0] = v0; acc[h2][bj][m][1] = v1;
	v_max_u32_sdwa v1, v182, v223 dst_sel:DWORD dst_unused:UNUSED_PAD src0_sel:BYTE_0 src1_sel:DWORD
	v_max_u32_sdwa v163, v182, v223 dst_sel:DWORD dst_unused:UNUSED_PAD src0_sel:BYTE_1 src1_sel:DWORD
	v_pk_mul_f32 v[164:165], v[164:165], v[168:169]
	v_cvt_f32_ubyte0_e32 v1, v1
	v_cvt_f32_ubyte0_e32 v163, v163
	v_pk_mul_f32 v[22:23], v[22:23], v[164:165]
	v_rcp_iflag_f32_e32 v162, v1
	v_rcp_iflag_f32_e32 v163, v163
	v_max_u32_sdwa v164, v182, v223 dst_sel:DWORD dst_unused:UNUSED_PAD src0_sel:BYTE_2 src1_sel:DWORD
	v_max_u32_sdwa v165, v182, v223 dst_sel:DWORD dst_unused:UNUSED_PAD src0_sel:BYTE_3 src1_sel:DWORD
	v_lshrrev_b32_e32 v1, 8, v180
	v_cvt_f32_ubyte0_e32 v164, v164
	v_cvt_f32_ubyte0_e32 v165, v165
	v_rcp_iflag_f32_e32 v164, v164
	v_rcp_iflag_f32_e32 v165, v165
	v_max_u32_sdwa v166, v180, v223 dst_sel:DWORD dst_unused:UNUSED_PAD src0_sel:BYTE_0 src1_sel:DWORD
	v_max_u32_sdwa v1, v1, v223 dst_sel:DWORD dst_unused:UNUSED_PAD src0_sel:BYTE_0 src1_sel:DWORD
	v_cvt_f32_ubyte0_e32 v167, v1
	v_cvt_f32_ubyte0_e32 v166, v166
	v_max_u32_sdwa v168, v180, v223 dst_sel:DWORD dst_unused:UNUSED_PAD src0_sel:BYTE_2 src1_sel:DWORD
	v_max_u32_sdwa v169, v180, v223 dst_sel:DWORD dst_unused:UNUSED_PAD src0_sel:BYTE_3 src1_sel:DWORD
	v_pk_mul_f32 v[162:163], v[162:163], v[166:167]
	v_cvt_f32_ubyte0_e32 v169, v169
	v_cvt_f32_ubyte0_e32 v168, v168
	v_pk_mul_f32 v[48:49], v[48:49], v[162:163]
	v_max_u32_sdwa v1, v183, v223 dst_sel:DWORD dst_unused:UNUSED_PAD src0_sel:BYTE_0 src1_sel:DWORD
	v_max_u32_sdwa v163, v183, v223 dst_sel:DWORD dst_unused:UNUSED_PAD src0_sel:BYTE_1 src1_sel:DWORD
	v_pk_mul_f32 v[164:165], v[164:165], v[168:169]
	v_cvt_f32_ubyte0_e32 v1, v1
	v_cvt_f32_ubyte0_e32 v163, v163
	v_pk_mul_f32 v[50:51], v[50:51], v[164:165]
	v_rcp_iflag_f32_e32 v162, v1
	v_rcp_iflag_f32_e32 v163, v163
	v_max_u32_sdwa v164, v183, v223 dst_sel:DWORD dst_unused:UNUSED_PAD src0_sel:BYTE_2 src1_sel:DWORD
	v_max_u32_sdwa v165, v183, v223 dst_sel:DWORD dst_unused:UNUSED_PAD src0_sel:BYTE_3 src1_sel:DWORD
	v_lshrrev_b32_e32 v1, 8, v181
	v_cvt_f32_ubyte0_e32 v164, v164
	v_cvt_f32_ubyte0_e32 v165, v165
	v_rcp_iflag_f32_e32 v164, v164
	v_rcp_iflag_f32_e32 v165, v165
	v_max_u32_sdwa v166, v181, v223 dst_sel:DWORD dst_unused:UNUSED_PAD src0_sel:BYTE_0 src1_sel:DWORD
	v_max_u32_sdwa v1, v1, v223 dst_sel:DWORD dst_unused:UNUSED_PAD src0_sel:BYTE_0 src1_sel:DWORD
	v_cvt_f32_ubyte0_e32 v167, v1
	v_cvt_f32_ubyte0_e32 v166, v166
	v_max_u32_sdwa v168, v181, v223 dst_sel:DWORD dst_unused:UNUSED_PAD src0_sel:BYTE_2 src1_sel:DWORD
	v_max_u32_sdwa v169, v181, v223 dst_sel:DWORD dst_unused:UNUSED_PAD src0_sel:BYTE_3 src1_sel:DWORD
	v_pk_mul_f32 v[162:163], v[162:163], v[166:167]
	v_cvt_f32_ubyte0_e32 v169, v169
	v_cvt_f32_ubyte0_e32 v168, v168
	v_pk_mul_f32 v[44:45], v[44:45], v[162:163]
	v_max_u32_sdwa v1, v178, v223 dst_sel:DWORD dst_unused:UNUSED_PAD src0_sel:BYTE_0 src1_sel:DWORD
	v_max_u32_sdwa v163, v178, v223 dst_sel:DWORD dst_unused:UNUSED_PAD src0_sel:BYTE_1 src1_sel:DWORD
	v_pk_mul_f32 v[164:165], v[164:165], v[168:169]
	v_cvt_f32_ubyte0_e32 v1, v1
	v_cvt_f32_ubyte0_e32 v163, v163
	v_pk_mul_f32 v[46:47], v[46:47], v[164:165]
	v_rcp_iflag_f32_e32 v162, v1
	v_rcp_iflag_f32_e32 v163, v163
	v_max_u32_sdwa v164, v178, v223 dst_sel:DWORD dst_unused:UNUSED_PAD src0_sel:BYTE_2 src1_sel:DWORD
	v_max_u32_sdwa v165, v178, v223 dst_sel:DWORD dst_unused:UNUSED_PAD src0_sel:BYTE_3 src1_sel:DWORD
	v_lshrrev_b32_e32 v1, 8, v2
	v_cvt_f32_ubyte0_e32 v164, v164
	v_cvt_f32_ubyte0_e32 v165, v165
	v_rcp_iflag_f32_e32 v164, v164
	v_rcp_iflag_f32_e32 v165, v165
	v_max_u32_sdwa v166, v2, v223 dst_sel:DWORD dst_unused:UNUSED_PAD src0_sel:BYTE_0 src1_sel:DWORD
	v_max_u32_sdwa v1, v1, v223 dst_sel:DWORD dst_unused:UNUSED_PAD src0_sel:BYTE_0 src1_sel:DWORD
	v_max_u32_sdwa v168, v2, v223 dst_sel:DWORD dst_unused:UNUSED_PAD src0_sel:BYTE_2 src1_sel:DWORD
	v_max_u32_sdwa v2, v2, v223 dst_sel:DWORD dst_unused:UNUSED_PAD src0_sel:BYTE_3 src1_sel:DWORD
	v_cvt_f32_ubyte0_e32 v167, v1
	v_cvt_f32_ubyte0_e32 v166, v166
	v_cvt_f32_ubyte0_e32 v169, v2
	v_max_u32_sdwa v2, v179, v223 dst_sel:DWORD dst_unused:UNUSED_PAD src0_sel:BYTE_1 src1_sel:DWORD
	v_pk_mul_f32 v[162:163], v[162:163], v[166:167]
	v_cvt_f32_ubyte0_e32 v2, v2
	v_cvt_f32_ubyte0_e32 v168, v168
	v_pk_mul_f32 v[16:17], v[16:17], v[162:163]
	v_rcp_iflag_f32_e32 v163, v2
	v_max_u32_sdwa v2, v179, v223 dst_sel:DWORD dst_unused:UNUSED_PAD src0_sel:BYTE_2 src1_sel:DWORD
	v_pk_mul_f32 v[164:165], v[164:165], v[168:169]
	v_cvt_f32_ubyte0_e32 v2, v2
	v_pk_mul_f32 v[18:19], v[18:19], v[164:165]
	v_max_u32_sdwa v1, v179, v223 dst_sel:DWORD dst_unused:UNUSED_PAD src0_sel:BYTE_0 src1_sel:DWORD
	v_rcp_iflag_f32_e32 v164, v2
	v_max_u32_sdwa v2, v179, v223 dst_sel:DWORD dst_unused:UNUSED_PAD src0_sel:BYTE_3 src1_sel:DWORD
	v_cvt_f32_ubyte0_e32 v1, v1
	v_cvt_f32_ubyte0_e32 v2, v2
	v_rcp_iflag_f32_e32 v162, v1
	v_rcp_iflag_f32_e32 v165, v2
	v_lshrrev_b32_e32 v1, 8, v3
	v_max_u32_sdwa v2, v3, v223 dst_sel:DWORD dst_unused:UNUSED_PAD src0_sel:BYTE_0 src1_sel:DWORD
	v_max_u32_sdwa v1, v1, v223 dst_sel:DWORD dst_unused:UNUSED_PAD src0_sel:BYTE_0 src1_sel:DWORD
	v_max_u32_sdwa v166, v3, v223 dst_sel:DWORD dst_unused:UNUSED_PAD src0_sel:BYTE_2 src1_sel:DWORD
	v_max_u32_sdwa v167, v3, v223 dst_sel:DWORD dst_unused:UNUSED_PAD src0_sel:BYTE_3 src1_sel:DWORD
	v_cvt_f32_ubyte0_e32 v3, v1
	v_cvt_f32_ubyte0_e32 v2, v2
	v_cvt_f32_ubyte0_e32 v167, v167
	v_cvt_f32_ubyte0_e32 v166, v166
	v_pk_mul_f32 v[2:3], v[162:163], v[2:3]
	v_pk_mul_f32 v[162:163], v[164:165], v[166:167]
	v_pk_mul_f32 v[12:13], v[12:13], v[2:3]
;     static __device__ __forceinline__ float gb(unsigned w, int sh) { return (float)max((w >> sh) & 0xffu, 1u); }
; template <class Epi, class Sched, bool ALIGN_EPI = false, bool SP2 = false>
; __device__ __forceinline__ void gemm_phase(PG8_LAS unsigned char* lds, const Gemm g, const Sched& S, const Epi& E) {
;     ...
;             E.chain(acc, cur, has_next, wr, wc, fr, fq); S.done(cur);
;             if (!has_next) break;
;     __device__ __forceinline__ void chain(f32x4 (&acc)[2][2][4][2], const pg8::Unit& u, bool has_next, int wr, int wc, int fr, int fq) const {
;     ...
;                 for (int m = 0; m < 4; ++m)
; #pragma unroll
;                     for (int bj = 0; bj < 2; ++bj) {
;                         const u32x2 a = ga[2 * m + bj], n = gn[2 * m + bj];
;                         f32x4 v0 = acc[h2][bj][m][0], v1 = acc[h2][bj][m][1];
;                         v0[0] *= gb(a.x, 0) * __builtin_amdgcn_rcpf(gb(n.x, 0)); v0[1] *= gb(a.x, 8) * __builtin_amdgcn_rcpf(gb(n.x, 8));
;                         v0[2] *= gb(a.x, 16) * __builtin_amdgcn_rcpf(gb(n.x, 16)); v0[3] *= gb(a.x, 24) * __builtin_amdgcn_rcpf(gb(n.x, 24));
;                         v1[0] *= gb(a.y, 0) * __builtin_amdgcn_rcpf(gb(n.y, 0)); v1[1] *= gb(a.y, 8) * __builtin_amdgcn_rcpf(gb(n.y, 8));
;                         v1[2] *= gb(a.y, 16) * __builtin_amdgcn_rcpf(gb(n.y, 16)); v1[3] *= gb(a.y, 24) * __builtin_amdgcn_rcpf(gb(n.y, 24));
;                         acc[h2][bj][m][0] = v0; acc[h2][bj][m][1] = v1;
	v_pk_mul_f32 v[14:15], v[14:15], v[162:163]
	v_max_u32_sdwa v1, v190, v223 dst_sel:DWORD dst_unused:UNUSED_PAD src0_sel:BYTE_0 src1_sel:DWORD
	v_max_u32_sdwa v3, v190, v223 dst_sel:DWORD dst_unused:UNUSED_PAD src0_sel:BYTE_1 src1_sel:DWORD
	v_max_u32_sdwa v162, v190, v223 dst_sel:DWORD dst_unused:UNUSED_PAD src0_sel:BYTE_2 src1_sel:DWORD
	v_max_u32_sdwa v163, v190, v223 dst_sel:DWORD dst_unused:UNUSED_PAD src0_sel:BYTE_3 src1_sel:DWORD
	v_cvt_f32_ubyte0_e32 v1, v1
	v_cvt_f32_ubyte0_e32 v3, v3
	v_cvt_f32_ubyte0_e32 v162, v162
	v_cvt_f32_ubyte0_e32 v163, v163
	v_rcp_iflag_f32_e32 v2, v1
	v_rcp_iflag_f32_e32 v3, v3
	v_rcp_iflag_f32_e32 v162, v162
	v_rcp_iflag_f32_e32 v163, v163
	v_lshrrev_b32_e32 v1, 8, v188
	v_max_u32_sdwa v164, v188, v223 dst_sel:DWORD dst_unused:UNUSED_PAD src0_sel:BYTE_0 src1_sel:DWORD
	v_max_u32_sdwa v1, v1, v223 dst_sel:DWORD dst_unused:UNUSED_PAD src0_sel:BYTE_0 src1_sel:DWORD
	v_max_u32_sdwa v166, v188, v223 dst_sel:DWORD dst_unused:UNUSED_PAD src0_sel:BYTE_2 src1_sel:DWORD
	v_max_u32_sdwa v167, v188, v223 dst_sel:DWORD dst_unused:UNUSED_PAD src0_sel:BYTE_3 src1_sel:DWORD
	v_cvt_f32_ubyte0_e32 v165, v1
	v_cvt_f32_ubyte0_e32 v164, v164
	v_cvt_f32_ubyte0_e32 v167, v167
	v_cvt_f32_ubyte0_e32 v166, v166
	v_pk_mul_f32 v[2:3], v[2:3], v[164:165]
	v_pk_mul_f32 v[162:163], v[162:163], v[166:167]
	v_pk_mul_f32 v[40:41], v[40:41], v[2:3]
	v_pk_mul_f32 v[42:43], v[42:43], v[162:163]
	v_max_u32_sdwa v1, v191, v223 dst_sel:DWORD dst_unused:UNUSED_PAD src0_sel:BYTE_0 src1_sel:DWORD
	v_max_u32_sdwa v3, v191, v223 dst_sel:DWORD dst_unused:UNUSED_PAD src0_sel:BYTE_1 src1_sel:DWORD
	v_max_u32_sdwa v162, v191, v223 dst_sel:DWORD dst_unused:UNUSED_PAD src0_sel:BYTE_2 src1_sel:DWORD
	v_max_u32_sdwa v163, v191, v223 dst_sel:DWORD dst_unused:UNUSED_PAD src0_sel:BYTE_3 src1_sel:DWORD
	v_cvt_f32_ubyte0_e32 v1, v1
	v_cvt_f32_ubyte0_e32 v3, v3
	v_cvt_f32_ubyte0_e32 v162, v162
	v_cvt_f32_ubyte0_e32 v163, v163
	v_rcp_iflag_f32_e32 v2, v1
	v_rcp_iflag_f32_e32 v3, v3
	v_rcp_iflag_f32_e32 v162, v162
	v_rcp_iflag_f32_e32 v163, v163
	v_lshrrev_b32_e32 v1, 8, v189
	v_max_u32_sdwa v164, v189, v223 dst_sel:DWORD dst_unused:UNUSED_PAD src0_sel:BYTE_0 src1_sel:DWORD
	v_max_u32_sdwa v1, v1, v223 dst_sel:DWORD dst_unused:UNUSED_PAD src0_sel:BYTE_0 src1_sel:DWORD
	v_max_u32_sdwa v166, v189, v223 dst_sel:DWORD dst_unused:UNUSED_PAD src0_sel:BYTE_2 src1_sel:DWORD
	v_max_u32_sdwa v167, v189, v223 dst_sel:DWORD dst_unused:UNUSED_PAD src0_sel:BYTE_3 src1_sel:DWORD
	v_cvt_f32_ubyte0_e32 v165, v1
	v_cvt_f32_ubyte0_e32 v164, v164
	v_cvt_f32_ubyte0_e32 v167, v167
	v_cvt_f32_ubyte0_e32 v166, v166
	v_pk_mul_f32 v[2:3], v[2:3], v[164:165]
	v_pk_mul_f32 v[162:163], v[162:163], v[166:167]
	v_pk_mul_f32 v[36:37], v[36:37], v[2:3]
	v_pk_mul_f32 v[38:39], v[38:39], v[162:163]
	v_max_u32_sdwa v1, v186, v223 dst_sel:DWORD dst_unused:UNUSED_PAD src0_sel:BYTE_0 src1_sel:DWORD
	v_max_u32_sdwa v3, v186, v223 dst_sel:DWORD dst_unused:UNUSED_PAD src0_sel:BYTE_1 src1_sel:DWORD
	v_max_u32_sdwa v162, v186, v223 dst_sel:DWORD dst_unused:UNUSED_PAD src0_sel:BYTE_2 src1_sel:DWORD
	v_max_u32_sdwa v163, v186, v223 dst_sel:DWORD dst_unused:UNUSED_PAD src0_sel:BYTE_3 src1_sel:DWORD
	v_cvt_f32_ubyte0_e32 v1, v1
	v_cvt_f32_ubyte0_e32 v3, v3
	v_cvt_f32_ubyte0_e32 v162, v162
	v_cvt_f32_ubyte0_e32 v163, v163
	v_rcp_iflag_f32_e32 v2, v1
	v_rcp_iflag_f32_e32 v3, v3
	v_rcp_iflag_f32_e32 v162, v162
	v_rcp_iflag_f32_e32 v163, v163
	v_lshrrev_b32_e32 v1, 8, v184
	v_max_u32_sdwa v164, v184, v223 dst_sel:DWORD dst_unused:UNUSED_PAD src0_sel:BYTE_0 src1_sel:DWORD
	v_max_u32_sdwa v1, v1, v223 dst_sel:DWORD dst_unused:UNUSED_PAD src0_sel:BYTE_0 src1_sel:DWORD
	v_max_u32_sdwa v166, v184, v223 dst_sel:DWORD dst_unused:UNUSED_PAD src0_sel:BYTE_2 src1_sel:DWORD
	v_max_u32_sdwa v167, v184, v223 dst_sel:DWORD dst_unused:UNUSED_PAD src0_sel:BYTE_3 src1_sel:DWORD
	v_cvt_f32_ubyte0_e32 v165, v1
	v_cvt_f32_ubyte0_e32 v164, v164
	v_cvt_f32_ubyte0_e32 v167, v167
	v_cvt_f32_ubyte0_e32 v166, v166
	v_pk_mul_f32 v[2:3], v[2:3], v[164:165]
	v_pk_mul_f32 v[162:163], v[162:163], v[166:167]
	v_pk_mul_f32 v[8:9], v[8:9], v[2:3]
	v_pk_mul_f32 v[10:11], v[10:11], v[162:163]
	v_max_u32_sdwa v1, v187, v223 dst_sel:DWORD dst_unused:UNUSED_PAD src0_sel:BYTE_0 src1_sel:DWORD
	v_max_u32_sdwa v3, v187, v223 dst_sel:DWORD dst_unused:UNUSED_PAD src0_sel:BYTE_1 src1_sel:DWORD
	v_max_u32_sdwa v162, v187, v223 dst_sel:DWORD dst_unused:UNUSED_PAD src0_sel:BYTE_2 src1_sel:DWORD
	v_max_u32_sdwa v163, v187, v223 dst_sel:DWORD dst_unused:UNUSED_PAD src0_sel:BYTE_3 src1_sel:DWORD
	v_cvt_f32_ubyte0_e32 v1, v1
	v_cvt_f32_ubyte0_e32 v3, v3
	v_cvt_f32_ubyte0_e32 v162, v162
	v_cvt_f32_ubyte0_e32 v163, v163
	v_rcp_iflag_f32_e32 v2, v1
	v_rcp_iflag_f32_e32 v3, v3
	v_rcp_iflag_f32_e32 v162, v162
	v_rcp_iflag_f32_e32 v163, v163
	v_lshrrev_b32_e32 v1, 8, v185
	v_max_u32_sdwa v164, v185, v223 dst_sel:DWORD dst_unused:UNUSED_PAD src0_sel:BYTE_0 src1_sel:DWORD
	v_max_u32_sdwa v1, v1, v223 dst_sel:DWORD dst_unused:UNUSED_PAD src0_sel:BYTE_0 src1_sel:DWORD
	v_max_u32_sdwa v166, v185, v223 dst_sel:DWORD dst_unused:UNUSED_PAD src0_sel:BYTE_2 src1_sel:DWORD
	v_max_u32_sdwa v167, v185, v223 dst_sel:DWORD dst_unused:UNUSED_PAD src0_sel:BYTE_3 src1_sel:DWORD
	v_cvt_f32_ubyte0_e32 v165, v1
	v_cvt_f32_ubyte0_e32 v164, v164
	v_cvt_f32_ubyte0_e32 v167, v167
	v_cvt_f32_ubyte0_e32 v166, v166
	v_pk_mul_f32 v[2:3], v[2:3], v[164:165]
	v_pk_mul_f32 v[162:163], v[162:163], v[166:167]
	v_pk_mul_f32 v[4:5], v[4:5], v[2:3]
	v_pk_mul_f32 v[6:7], v[6:7], v[162:163]
	s_cmp_eq_u32 s42, 2
	s_mov_b64 s[16:17], -1
	s_cbranch_scc1 .LBB0_1028
